# removed the 20 redundant s_waitcnt lgkmcnt(0) between the sub-phase barrier and its first MFMA (already waited before the barrier)
# baseline (speedup 1.0000x reference)
; #define PG8_STAGE(bufoff, gbase, voff) do { _Pragma("unroll") for (int _i = 0; _i < 2; ++_i) \
;         __builtin_amdgcn_global_load_lds((const unsigned*)((const char*)(gbase) + (voff)[_i]), (LAS unsigned*)(lds + (bufoff) + ldsw + _i * 8192), 16, 0, 0); } while (0)
; #define PG8_LDA(dst, b, h) do { _Pragma("unroll") for (int m = 0; m < 4; ++m) _Pragma("unroll") for (int k = 0; k < 2; ++k) dst[m][k] = *(const LAS bf16x8*)(lds + PG8_SA(b, h) + aoff + m * 2048 + k * 1024); } while (0)
; #define PG8_LDB(dst, b, h) do { _Pragma("unroll") for (int n = 0; n < 2; ++n) _Pragma("unroll") for (int k = 0; k < 2; ++k) dst[n][k] = *(const LAS bf16x8*)(lds + PG8_SB(b, h) + boff + n * 2048 + k * 1024); } while (0)
; #define PG8_MMA(ai, bj, At, Bt) do { __builtin_amdgcn_s_setprio(1); _Pragma("unroll") for (int m = 0; m < 4; ++m) _Pragma("unroll") for (int n = 0; n < 2; ++n) _Pragma("unroll") for (int k = 0; k < 2; ++k) \
;         acc[ai][bj][m][n] = __builtin_amdgcn_mfma_f32_16x16x32_bf16(Bt[n][k], At[m][k], acc[ai][bj][m][n], 0, 0, 0); __builtin_amdgcn_s_setprio(0); } while (0)
; #define PG8_WAIT_V(n) asm volatile("s_waitcnt vmcnt(" #n ")" ::: "memory")
; #define PG8_WAIT_L(n) asm volatile("s_waitcnt lgkmcnt(" #n ")" ::: "memory")
; #define PG8_BAR __builtin_amdgcn_s_barrier()
; #define PG8_SCHED __builtin_amdgcn_sched_barrier(0)
; template <class Epi, class Sched>
; DI void gemm_phase(const int wv, LAS unsigned char* lds, const int lda, const int ldb, const int K, const Sched& S, const Epi& E) {
;     ...
;             const char* a1 = cA + (size_t)(t + 1) * kstep;
;             const char* a2 = last ? nA : cA + (size_t)(t + 2) * kstep; const char* b2 = last ? nB : cB + (size_t)(t + 2) * kstep;
;             const char* a3 = a2 + kstep; const char* b3 = b2 + kstep;
;             PG8_LDB(B0, 0, 0); PG8_LDB(B1, 0, 1); PG8_SCHED; PG8_LDA(At, 0, 0); PG8_STAGE(PG8_SA(1, 1), a1 + hstepA, voffA);
;             PG8_WAIT_V(8); PG8_WAIT_L(0); PG8_BAR; PG8_MMA(0, 0, At, B0); PG8_MMA(0, 1, At, B1); PG8_BAR; PG8_SCHED;
;             PG8_LDA(At, 0, 1); PG8_STAGE(PG8_SB(0, 0), b2, voffB); PG8_STAGE(PG8_SB(0, 1), b2 + hstepB, voffB); PG8_STAGE(PG8_SA(0, 0), a2, voffA);
;             PG8_WAIT_V(8); PG8_WAIT_L(0); PG8_BAR; PG8_MMA(1, 0, At, B0); PG8_MMA(1, 1, At, B1); PG8_BAR; PG8_SCHED;
.LBB0_285:
	s_add_u32 s20, s18, 0xfff80080
	s_addc_u32 s21, s19, -1
	s_add_i32 s42, 0, 0x10000
	s_cmp_eq_u32 s41, 28
	s_cselect_b32 s23, s15, s21
	s_cselect_b32 s22, s14, s20
	v_add_u32_e32 v143, s42, v139
	s_cselect_b32 s21, s17, s40
	s_cselect_b32 s20, s16, s13
	s_add_i32 s44, 0, 0x14000
	ds_read_b128 v[144:147], v143
	ds_read_b128 v[148:151], v143 offset:1024
	ds_read_b128 v[152:155], v143 offset:2048
	ds_read_b128 v[156:159], v143 offset:3072
	v_add_u32_e32 v143, s44, v139
	ds_read_b128 v[168:171], v143
	ds_read_b128 v[172:175], v143 offset:1024
	ds_read_b128 v[176:179], v143 offset:2048
	ds_read_b128 v[180:183], v143 offset:3072
	v_lshl_add_u64 v[162:163], s[18:19], 0, v[136:137]
	s_add_i32 m0, s29, 0xc000
	ds_read_b128 v[184:187], v142
	ds_read_b128 v[188:191], v142 offset:1024
	ds_read_b128 v[192:195], v142 offset:2048
	ds_read_b128 v[196:199], v142 offset:3072
	ds_read_b128 v[210:213], v142 offset:4096
	ds_read_b128 v[214:217], v142 offset:5120
	ds_read_b128 v[218:221], v142 offset:6144
	ds_read_b128 v[222:225], v142 offset:7168
	global_load_lds_dwordx4 v[162:163], off
	v_lshl_add_u64 v[162:163], s[18:19], 0, v[134:135]
	s_add_i32 m0, s29, 0xe000
	s_nop 0
	global_load_lds_dwordx4 v[162:163], off
	s_waitcnt vmcnt(8)
	s_waitcnt lgkmcnt(0)
	s_barrier
	s_setprio 1
	v_mfma_f32_16x16x32_bf16 v[124:127], v[144:147], v[184:187], v[124:127]
	v_mfma_f32_16x16x32_bf16 v[120:123], v[152:155], v[184:187], v[120:123]
	v_mfma_f32_16x16x32_bf16 v[116:119], v[144:147], v[192:195], v[116:119]
	v_mfma_f32_16x16x32_bf16 v[112:115], v[152:155], v[192:195], v[112:115]
	v_mfma_f32_16x16x32_bf16 v[100:103], v[144:147], v[210:213], v[100:103]
	v_mfma_f32_16x16x32_bf16 v[96:99], v[152:155], v[210:213], v[96:99]
	v_mfma_f32_16x16x32_bf16 v[88:91], v[144:147], v[218:221], v[88:91]
	v_mfma_f32_16x16x32_bf16 v[80:83], v[152:155], v[218:221], v[80:83]
	v_mfma_f32_16x16x32_bf16 v[124:127], v[148:151], v[188:191], v[124:127]
	v_mfma_f32_16x16x32_bf16 v[120:123], v[156:159], v[188:191], v[120:123]
	v_mfma_f32_16x16x32_bf16 v[116:119], v[148:151], v[196:199], v[116:119]
	v_mfma_f32_16x16x32_bf16 v[112:115], v[156:159], v[196:199], v[112:115]
	v_mfma_f32_16x16x32_bf16 v[100:103], v[148:151], v[214:217], v[100:103]
	v_mfma_f32_16x16x32_bf16 v[96:99], v[156:159], v[214:217], v[96:99]
	v_mfma_f32_16x16x32_bf16 v[88:91], v[148:151], v[222:225], v[88:91]
	v_mfma_f32_16x16x32_bf16 v[80:83], v[156:159], v[222:225], v[80:83]
	v_mfma_f32_16x16x32_bf16 v[108:111], v[168:171], v[184:187], v[108:111]
	v_mfma_f32_16x16x32_bf16 v[104:107], v[176:179], v[184:187], v[104:107]
	v_mfma_f32_16x16x32_bf16 v[92:95], v[168:171], v[192:195], v[92:95]
	v_mfma_f32_16x16x32_bf16 v[84:87], v[176:179], v[192:195], v[84:87]
	v_mfma_f32_16x16x32_bf16 v[76:79], v[168:171], v[210:213], v[76:79]
	v_mfma_f32_16x16x32_bf16 v[72:75], v[176:179], v[210:213], v[72:75]
	v_mfma_f32_16x16x32_bf16 v[68:71], v[168:171], v[218:221], v[68:71]
	v_mfma_f32_16x16x32_bf16 v[64:67], v[176:179], v[218:221], v[64:67]
	v_mfma_f32_16x16x32_bf16 v[108:111], v[172:175], v[188:191], v[108:111]
	v_mfma_f32_16x16x32_bf16 v[104:107], v[180:183], v[188:191], v[104:107]
	v_mfma_f32_16x16x32_bf16 v[92:95], v[172:175], v[196:199], v[92:95]
	v_mfma_f32_16x16x32_bf16 v[84:87], v[180:183], v[196:199], v[84:87]
	v_mfma_f32_16x16x32_bf16 v[76:79], v[172:175], v[214:217], v[76:79]
	v_mfma_f32_16x16x32_bf16 v[72:75], v[180:183], v[214:217], v[72:75]
	v_mfma_f32_16x16x32_bf16 v[68:71], v[172:175], v[222:225], v[68:71]
	v_mfma_f32_16x16x32_bf16 v[64:67], v[180:183], v[222:225], v[64:67]
	s_setprio 0
	s_barrier
	s_add_i32 s42, s42, s28
	v_lshl_add_u64 v[162:163], s[20:21], 0, v[160:161]
	s_mov_b32 m0, s42
	ds_read_b128 v[184:187], v142 offset:16384
	ds_read_b128 v[188:191], v142 offset:17408
	ds_read_b128 v[192:195], v142 offset:18432
	ds_read_b128 v[196:199], v142 offset:19456
	ds_read_b128 v[210:213], v142 offset:20480
	ds_read_b128 v[214:217], v142 offset:21504
	ds_read_b128 v[218:221], v142 offset:22528
	ds_read_b128 v[222:225], v142 offset:23552
	global_load_lds_dwordx4 v[162:163], off
	s_add_i32 m0, s42, 0x2000
	s_add_u32 s42, s20, 0x80000
	v_lshl_add_u64 v[164:165], s[20:21], 0, v[128:129]
	s_addc_u32 s43, s21, 0
	s_add_i32 s44, s44, s28
	global_load_lds_dwordx4 v[164:165], off
	v_lshl_add_u64 v[226:227], s[42:43], 0, v[160:161]
	s_mov_b32 m0, s44
	v_lshl_add_u64 v[228:229], s[22:23], 0, v[130:131]
	global_load_lds_dwordx4 v[226:227], off
	v_lshl_add_u64 v[226:227], s[42:43], 0, v[128:129]
	s_add_i32 m0, s44, 0x2000
	s_nop 0
	global_load_lds_dwordx4 v[226:227], off
	v_lshl_add_u64 v[226:227], s[22:23], 0, v[132:133]
	s_mov_b32 m0, s29
	s_nop 0
	global_load_lds_dwordx4 v[226:227], off
	s_mov_b32 m0, s30
	s_nop 0
	global_load_lds_dwordx4 v[228:229], off
	s_waitcnt vmcnt(8)
	s_waitcnt lgkmcnt(0)
	s_barrier
; #define PG8_STAGE(bufoff, gbase, voff) do { _Pragma("unroll") for (int _i = 0; _i < 2; ++_i) \
;         __builtin_amdgcn_global_load_lds((const unsigned*)((const char*)(gbase) + (voff)[_i]), (LAS unsigned*)(lds + (bufoff) + ldsw + _i * 8192), 16, 0, 0); } while (0)
; #define PG8_LDA(dst, b, h) do { _Pragma("unroll") for (int m = 0; m < 4; ++m) _Pragma("unroll") for (int k = 0; k < 2; ++k) dst[m][k] = *(const LAS bf16x8*)(lds + PG8_SA(b, h) + aoff + m * 2048 + k * 1024); } while (0)
; #define PG8_LDB(dst, b, h) do { _Pragma("unroll") for (int n = 0; n < 2; ++n) _Pragma("unroll") for (int k = 0; k < 2; ++k) dst[n][k] = *(const LAS bf16x8*)(lds + PG8_SB(b, h) + boff + n * 2048 + k * 1024); } while (0)
; #define PG8_MMA(ai, bj, At, Bt) do { __builtin_amdgcn_s_setprio(1); _Pragma("unroll") for (int m = 0; m < 4; ++m) _Pragma("unroll") for (int n = 0; n < 2; ++n) _Pragma("unroll") for (int k = 0; k < 2; ++k) \
;         acc[ai][bj][m][n] = __builtin_amdgcn_mfma_f32_16x16x32_bf16(Bt[n][k], At[m][k], acc[ai][bj][m][n], 0, 0, 0); __builtin_amdgcn_s_setprio(0); } while (0)
; #define PG8_WAIT_V(n) asm volatile("s_waitcnt vmcnt(" #n ")" ::: "memory")
; #define PG8_WAIT_L(n) asm volatile("s_waitcnt lgkmcnt(" #n ")" ::: "memory")
; #define PG8_BAR __builtin_amdgcn_s_barrier()
; #define PG8_SCHED __builtin_amdgcn_sched_barrier(0)
; template <class Epi, class Sched>
; DI void gemm_phase(const int wv, LAS unsigned char* lds, const int lda, const int ldb, const int K, const Sched& S, const Epi& E) {
;     ...
;             PG8_WAIT_V(8); PG8_WAIT_L(0); PG8_BAR; PG8_MMA(1, 0, At, B0); PG8_MMA(1, 1, At, B1); PG8_BAR; PG8_SCHED;
;             PG8_LDB(B0, 1, 0); PG8_LDB(B1, 1, 1); PG8_SCHED; PG8_LDA(At, 1, 0); PG8_STAGE(PG8_SA(0, 1), a2 + hstepA, voffA);
;             PG8_WAIT_V(8); PG8_WAIT_L(0); PG8_BAR; PG8_MMA(0, 0, At, B0); PG8_MMA(0, 1, At, B1); PG8_BAR; PG8_SCHED;
	s_setprio 1
	v_mfma_f32_16x16x32_bf16 v[60:63], v[144:147], v[184:187], v[60:63]
	v_mfma_f32_16x16x32_bf16 v[56:59], v[152:155], v[184:187], v[56:59]
	v_mfma_f32_16x16x32_bf16 v[52:55], v[144:147], v[192:195], v[52:55]
	v_mfma_f32_16x16x32_bf16 v[48:51], v[152:155], v[192:195], v[48:51]
	v_mfma_f32_16x16x32_bf16 v[44:47], v[144:147], v[210:213], v[44:47]
	v_mfma_f32_16x16x32_bf16 v[36:39], v[152:155], v[210:213], v[36:39]
	v_mfma_f32_16x16x32_bf16 v[28:31], v[144:147], v[218:221], v[28:31]
	v_mfma_f32_16x16x32_bf16 v[20:23], v[152:155], v[218:221], v[20:23]
	v_mfma_f32_16x16x32_bf16 v[60:63], v[148:151], v[188:191], v[60:63]
	v_mfma_f32_16x16x32_bf16 v[56:59], v[156:159], v[188:191], v[56:59]
	v_mfma_f32_16x16x32_bf16 v[52:55], v[148:151], v[196:199], v[52:55]
	v_mfma_f32_16x16x32_bf16 v[48:51], v[156:159], v[196:199], v[48:51]
	v_mfma_f32_16x16x32_bf16 v[44:47], v[148:151], v[214:217], v[44:47]
	v_mfma_f32_16x16x32_bf16 v[36:39], v[156:159], v[214:217], v[36:39]
	v_mfma_f32_16x16x32_bf16 v[28:31], v[148:151], v[222:225], v[28:31]
	v_mfma_f32_16x16x32_bf16 v[20:23], v[156:159], v[222:225], v[20:23]
	v_mfma_f32_16x16x32_bf16 v[40:43], v[168:171], v[184:187], v[40:43]
	v_mfma_f32_16x16x32_bf16 v[32:35], v[176:179], v[184:187], v[32:35]
	v_mfma_f32_16x16x32_bf16 v[24:27], v[168:171], v[192:195], v[24:27]
	v_mfma_f32_16x16x32_bf16 v[16:19], v[176:179], v[192:195], v[16:19]
	v_mfma_f32_16x16x32_bf16 v[12:15], v[168:171], v[210:213], v[12:15]
	v_mfma_f32_16x16x32_bf16 v[8:11], v[176:179], v[210:213], v[8:11]
	v_mfma_f32_16x16x32_bf16 v[4:7], v[168:171], v[218:221], v[4:7]
	v_mfma_f32_16x16x32_bf16 v[0:3], v[176:179], v[218:221], v[0:3]
	v_mfma_f32_16x16x32_bf16 v[40:43], v[172:175], v[188:191], v[40:43]
	v_mfma_f32_16x16x32_bf16 v[32:35], v[180:183], v[188:191], v[32:35]
	v_mfma_f32_16x16x32_bf16 v[24:27], v[172:175], v[196:199], v[24:27]
	v_mfma_f32_16x16x32_bf16 v[16:19], v[180:183], v[196:199], v[16:19]
	v_mfma_f32_16x16x32_bf16 v[12:15], v[172:175], v[214:217], v[12:15]
	v_mfma_f32_16x16x32_bf16 v[8:11], v[180:183], v[214:217], v[8:11]
	v_mfma_f32_16x16x32_bf16 v[4:7], v[172:175], v[222:225], v[4:7]
	v_mfma_f32_16x16x32_bf16 v[0:3], v[180:183], v[222:225], v[0:3]
	s_setprio 0
	s_barrier
	s_add_i32 s42, 0, 0x18000
	v_add_u32_e32 v143, s42, v139
	s_add_i32 s43, 0, 0x1c000
	ds_read_b128 v[144:147], v143
	ds_read_b128 v[148:151], v143 offset:1024
	ds_read_b128 v[152:155], v143 offset:2048
	ds_read_b128 v[156:159], v143 offset:3072
	v_add_u32_e32 v143, s43, v139
	ds_read_b128 v[168:171], v143
	ds_read_b128 v[172:175], v143 offset:1024
	ds_read_b128 v[176:179], v143 offset:2048
	ds_read_b128 v[180:183], v143 offset:3072
	s_add_u32 s22, s22, 0x80000
	s_addc_u32 s23, s23, 0
	s_mov_b32 m0, s31
	v_lshl_add_u64 v[230:231], s[22:23], 0, v[132:133]
	ds_read_b128 v[184:187], v142 offset:32768
	ds_read_b128 v[188:191], v142 offset:33792
	ds_read_b128 v[192:195], v142 offset:34816
	ds_read_b128 v[196:199], v142 offset:35840
	ds_read_b128 v[210:213], v142 offset:36864
	ds_read_b128 v[214:217], v142 offset:37888
	ds_read_b128 v[218:221], v142 offset:38912
	ds_read_b128 v[222:225], v142 offset:39936
	global_load_lds_dwordx4 v[230:231], off
	v_lshl_add_u64 v[230:231], s[22:23], 0, v[130:131]
	s_mov_b32 m0, s34
	s_nop 0
	global_load_lds_dwordx4 v[230:231], off
	s_waitcnt vmcnt(8)
	s_waitcnt lgkmcnt(0)
	s_barrier
	s_setprio 1
	v_mfma_f32_16x16x32_bf16 v[124:127], v[144:147], v[184:187], v[124:127]
	v_mfma_f32_16x16x32_bf16 v[120:123], v[152:155], v[184:187], v[120:123]
	v_mfma_f32_16x16x32_bf16 v[116:119], v[144:147], v[192:195], v[116:119]
	v_mfma_f32_16x16x32_bf16 v[112:115], v[152:155], v[192:195], v[112:115]
	v_mfma_f32_16x16x32_bf16 v[100:103], v[144:147], v[210:213], v[100:103]
	v_mfma_f32_16x16x32_bf16 v[96:99], v[152:155], v[210:213], v[96:99]
	v_mfma_f32_16x16x32_bf16 v[88:91], v[144:147], v[218:221], v[88:91]
	v_mfma_f32_16x16x32_bf16 v[80:83], v[152:155], v[218:221], v[80:83]
	v_mfma_f32_16x16x32_bf16 v[124:127], v[148:151], v[188:191], v[124:127]
	v_mfma_f32_16x16x32_bf16 v[120:123], v[156:159], v[188:191], v[120:123]
	v_mfma_f32_16x16x32_bf16 v[116:119], v[148:151], v[196:199], v[116:119]
	v_mfma_f32_16x16x32_bf16 v[112:115], v[156:159], v[196:199], v[112:115]
	v_mfma_f32_16x16x32_bf16 v[100:103], v[148:151], v[214:217], v[100:103]
	v_mfma_f32_16x16x32_bf16 v[96:99], v[156:159], v[214:217], v[96:99]
	v_mfma_f32_16x16x32_bf16 v[88:91], v[148:151], v[222:225], v[88:91]
	v_mfma_f32_16x16x32_bf16 v[80:83], v[156:159], v[222:225], v[80:83]
	v_mfma_f32_16x16x32_bf16 v[108:111], v[168:171], v[184:187], v[108:111]
	v_mfma_f32_16x16x32_bf16 v[104:107], v[176:179], v[184:187], v[104:107]
	v_mfma_f32_16x16x32_bf16 v[92:95], v[168:171], v[192:195], v[92:95]
	v_mfma_f32_16x16x32_bf16 v[84:87], v[176:179], v[192:195], v[84:87]
	v_mfma_f32_16x16x32_bf16 v[76:79], v[168:171], v[210:213], v[76:79]
	v_mfma_f32_16x16x32_bf16 v[72:75], v[176:179], v[210:213], v[72:75]
	v_mfma_f32_16x16x32_bf16 v[68:71], v[168:171], v[218:221], v[68:71]
	v_mfma_f32_16x16x32_bf16 v[64:67], v[176:179], v[218:221], v[64:67]
	v_mfma_f32_16x16x32_bf16 v[108:111], v[172:175], v[188:191], v[108:111]
	v_mfma_f32_16x16x32_bf16 v[104:107], v[180:183], v[188:191], v[104:107]
	v_mfma_f32_16x16x32_bf16 v[92:95], v[172:175], v[196:199], v[92:95]
	v_mfma_f32_16x16x32_bf16 v[84:87], v[180:183], v[196:199], v[84:87]
	v_mfma_f32_16x16x32_bf16 v[76:79], v[172:175], v[214:217], v[76:79]
	v_mfma_f32_16x16x32_bf16 v[72:75], v[180:183], v[214:217], v[72:75]
	v_mfma_f32_16x16x32_bf16 v[68:71], v[172:175], v[222:225], v[68:71]
	v_mfma_f32_16x16x32_bf16 v[64:67], v[180:183], v[222:225], v[64:67]
	s_setprio 0
	s_barrier
; #define PG8_STAGE(bufoff, gbase, voff) do { _Pragma("unroll") for (int _i = 0; _i < 2; ++_i) \
;         __builtin_amdgcn_global_load_lds((const unsigned*)((const char*)(gbase) + (voff)[_i]), (LAS unsigned*)(lds + (bufoff) + ldsw + _i * 8192), 16, 0, 0); } while (0)
; #define PG8_LDA(dst, b, h) do { _Pragma("unroll") for (int m = 0; m < 4; ++m) _Pragma("unroll") for (int k = 0; k < 2; ++k) dst[m][k] = *(const LAS bf16x8*)(lds + PG8_SA(b, h) + aoff + m * 2048 + k * 1024); } while (0)
; #define PG8_MMA(ai, bj, At, Bt) do { __builtin_amdgcn_s_setprio(1); _Pragma("unroll") for (int m = 0; m < 4; ++m) _Pragma("unroll") for (int n = 0; n < 2; ++n) _Pragma("unroll") for (int k = 0; k < 2; ++k) \
;         acc[ai][bj][m][n] = __builtin_amdgcn_mfma_f32_16x16x32_bf16(Bt[n][k], At[m][k], acc[ai][bj][m][n], 0, 0, 0); __builtin_amdgcn_s_setprio(0); } while (0)
; #define PG8_WAIT_V(n) asm volatile("s_waitcnt vmcnt(" #n ")" ::: "memory")
; #define PG8_WAIT_L(n) asm volatile("s_waitcnt lgkmcnt(" #n ")" ::: "memory")
; #define PG8_BAR __builtin_amdgcn_s_barrier()
; #define PG8_SCHED __builtin_amdgcn_sched_barrier(0)
; template <class Epi, class Sched>
; DI void gemm_phase(const int wv, LAS unsigned char* lds, const int lda, const int ldb, const int K, const Sched& S, const Epi& E) {
;     ...
;             PG8_LDA(At, 1, 1); PG8_STAGE(PG8_SB(1, 0), b3, voffB); PG8_STAGE(PG8_SB(1, 1), b3 + hstepB, voffB); PG8_STAGE(PG8_SA(1, 0), a3, voffA);
;             PG8_WAIT_V(8); PG8_WAIT_L(0); PG8_BAR; PG8_MMA(1, 0, At, B0); PG8_MMA(1, 1, At, B1); PG8_BAR; PG8_SCHED;
;         }
;         if (wr == 0) PG8_BAR;
	s_add_i32 s22, s42, s28
	v_lshl_add_u64 v[162:163], v[162:163], 0, s[78:79]
	s_mov_b32 m0, s22
	ds_read_b128 v[184:187], v142 offset:49152
	ds_read_b128 v[188:191], v142 offset:50176
	ds_read_b128 v[192:195], v142 offset:51200
	ds_read_b128 v[196:199], v142 offset:52224
	ds_read_b128 v[210:213], v142 offset:53248
	ds_read_b128 v[214:217], v142 offset:54272
	ds_read_b128 v[218:221], v142 offset:55296
	ds_read_b128 v[222:225], v142 offset:56320
	global_load_lds_dwordx4 v[162:163], off
	s_add_i32 m0, s22, 0x2000
	s_add_u32 s20, s20, 0x80080
	v_lshl_add_u64 v[162:163], v[164:165], 0, s[78:79]
	s_addc_u32 s21, s21, 0
	s_add_i32 s22, s43, s28
	global_load_lds_dwordx4 v[162:163], off
	v_lshl_add_u64 v[162:163], s[20:21], 0, v[160:161]
	s_mov_b32 m0, s22
	s_nop 0
	global_load_lds_dwordx4 v[162:163], off
	v_lshl_add_u64 v[162:163], s[20:21], 0, v[128:129]
	s_add_i32 m0, s22, 0x2000
	s_nop 0
	global_load_lds_dwordx4 v[162:163], off
	v_lshl_add_u64 v[162:163], v[226:227], 0, s[78:79]
	s_mov_b32 m0, s35
	s_nop 0
	global_load_lds_dwordx4 v[162:163], off
	v_lshl_add_u64 v[162:163], v[228:229], 0, s[78:79]
	s_mov_b32 m0, s36
	s_nop 0
	global_load_lds_dwordx4 v[162:163], off
	s_waitcnt vmcnt(8)
	s_waitcnt lgkmcnt(0)
	s_barrier
	s_setprio 1
	v_mfma_f32_16x16x32_bf16 v[60:63], v[144:147], v[184:187], v[60:63]
	v_mfma_f32_16x16x32_bf16 v[56:59], v[152:155], v[184:187], v[56:59]
	v_mfma_f32_16x16x32_bf16 v[52:55], v[144:147], v[192:195], v[52:55]
	v_mfma_f32_16x16x32_bf16 v[48:51], v[152:155], v[192:195], v[48:51]
	v_mfma_f32_16x16x32_bf16 v[44:47], v[144:147], v[210:213], v[44:47]
	v_mfma_f32_16x16x32_bf16 v[36:39], v[152:155], v[210:213], v[36:39]
	v_mfma_f32_16x16x32_bf16 v[28:31], v[144:147], v[218:221], v[28:31]
	v_mfma_f32_16x16x32_bf16 v[20:23], v[152:155], v[218:221], v[20:23]
	v_mfma_f32_16x16x32_bf16 v[60:63], v[148:151], v[188:191], v[60:63]
	v_mfma_f32_16x16x32_bf16 v[56:59], v[156:159], v[188:191], v[56:59]
	v_mfma_f32_16x16x32_bf16 v[52:55], v[148:151], v[196:199], v[52:55]
	v_mfma_f32_16x16x32_bf16 v[48:51], v[156:159], v[196:199], v[48:51]
	v_mfma_f32_16x16x32_bf16 v[44:47], v[148:151], v[214:217], v[44:47]
	v_mfma_f32_16x16x32_bf16 v[36:39], v[156:159], v[214:217], v[36:39]
	v_mfma_f32_16x16x32_bf16 v[28:31], v[148:151], v[222:225], v[28:31]
	v_mfma_f32_16x16x32_bf16 v[20:23], v[156:159], v[222:225], v[20:23]
	v_mfma_f32_16x16x32_bf16 v[40:43], v[168:171], v[184:187], v[40:43]
	v_mfma_f32_16x16x32_bf16 v[32:35], v[176:179], v[184:187], v[32:35]
	v_mfma_f32_16x16x32_bf16 v[24:27], v[168:171], v[192:195], v[24:27]
	v_mfma_f32_16x16x32_bf16 v[16:19], v[176:179], v[192:195], v[16:19]
	v_mfma_f32_16x16x32_bf16 v[12:15], v[168:171], v[210:213], v[12:15]
	v_mfma_f32_16x16x32_bf16 v[8:11], v[176:179], v[210:213], v[8:11]
	v_mfma_f32_16x16x32_bf16 v[4:7], v[168:171], v[218:221], v[4:7]
	v_mfma_f32_16x16x32_bf16 v[0:3], v[176:179], v[218:221], v[0:3]
	v_mfma_f32_16x16x32_bf16 v[40:43], v[172:175], v[188:191], v[40:43]
	v_mfma_f32_16x16x32_bf16 v[32:35], v[180:183], v[188:191], v[32:35]
	v_mfma_f32_16x16x32_bf16 v[24:27], v[172:175], v[196:199], v[24:27]
	v_mfma_f32_16x16x32_bf16 v[16:19], v[180:183], v[196:199], v[16:19]
	v_mfma_f32_16x16x32_bf16 v[12:15], v[172:175], v[214:217], v[12:15]
	v_mfma_f32_16x16x32_bf16 v[8:11], v[180:183], v[214:217], v[8:11]
	v_mfma_f32_16x16x32_bf16 v[4:7], v[172:175], v[222:225], v[4:7]
	v_mfma_f32_16x16x32_bf16 v[0:3], v[180:183], v[222:225], v[0:3]
	s_setprio 0
	s_barrier
	s_add_i32 s41, s41, 2
	s_add_u32 s13, s13, 0x100
	s_addc_u32 s40, s40, 0
	s_add_u32 s18, s18, 0x100
	s_addc_u32 s19, s19, 0
	s_cmp_gt_u32 s41, 29
	s_cbranch_scc0 .LBB0_285
	s_and_b64 vcc, exec, s[10:11]
	s_cbranch_vccz .LBB0_288
	s_barrier

; #define PG8_STAGE(bufoff, gbase, voff) do { _Pragma("unroll") for (int _i = 0; _i < 2; ++_i) \
;         __builtin_amdgcn_global_load_lds((const unsigned*)((const char*)(gbase) + (voff)[_i]), (LAS unsigned*)(lds + (bufoff) + ldsw + _i * 8192), 16, 0, 0); } while (0)
; #define PG8_LDA(dst, b, h) do { _Pragma("unroll") for (int m = 0; m < 4; ++m) _Pragma("unroll") for (int k = 0; k < 2; ++k) dst[m][k] = *(const LAS bf16x8*)(lds + PG8_SA(b, h) + aoff + m * 2048 + k * 1024); } while (0)
; #define PG8_LDB(dst, b, h) do { _Pragma("unroll") for (int n = 0; n < 2; ++n) _Pragma("unroll") for (int k = 0; k < 2; ++k) dst[n][k] = *(const LAS bf16x8*)(lds + PG8_SB(b, h) + boff + n * 2048 + k * 1024); } while (0)
; #define PG8_MMA(ai, bj, At, Bt) do { __builtin_amdgcn_s_setprio(1); _Pragma("unroll") for (int m = 0; m < 4; ++m) _Pragma("unroll") for (int n = 0; n < 2; ++n) _Pragma("unroll") for (int k = 0; k < 2; ++k) \
;         acc[ai][bj][m][n] = __builtin_amdgcn_mfma_f32_16x16x32_bf16(Bt[n][k], At[m][k], acc[ai][bj][m][n], 0, 0, 0); __builtin_amdgcn_s_setprio(0); } while (0)
; #define PG8_WAIT_V(n) asm volatile("s_waitcnt vmcnt(" #n ")" ::: "memory")
; template <class Epi, class Sched>
; DI void gemm_phase(const int wv, LAS unsigned char* lds, const int lda, const int ldb, const int K, const Sched& S, const Epi& E) {
;     ...
;         const bool has_next = S.next(ui + 1, nxt);
;         const char* nA = has_next ? nxt.a : cA; const char* nB = has_next ? nxt.b : cB;
; #pragma unroll 1
;         for (int t = 0; t < nt; t += 2) {
;             const bool last = (t == nt - 2);
;             const char* a1 = cA + (size_t)(t + 1) * kstep;
;             const char* a2 = last ? nA : cA + (size_t)(t + 2) * kstep; const char* b2 = last ? nB : cB + (size_t)(t + 2) * kstep;
;             const char* a3 = a2 + kstep; const char* b3 = b2 + kstep;
;             PG8_LDB(B0, 0, 0); PG8_LDB(B1, 0, 1); PG8_SCHED; PG8_LDA(At, 0, 0); PG8_STAGE(PG8_SA(1, 1), a1 + hstepA, voffA);
;             PG8_WAIT_V(8); PG8_WAIT_L(0); PG8_BAR; PG8_MMA(0, 0, At, B0); PG8_MMA(0, 1, At, B1); PG8_BAR; PG8_SCHED;
;             PG8_LDA(At, 0, 1); PG8_STAGE(PG8_SB(0, 0), b2, voffB); PG8_STAGE(PG8_SB(0, 1), b2 + hstepB, voffB); PG8_STAGE(PG8_SA(0, 0), a2, voffA);
;             PG8_WAIT_V(8); PG8_WAIT_L(0); PG8_BAR; PG8_MMA(1, 0, At, B0); PG8_MMA(1, 1, At, B1); PG8_BAR; PG8_SCHED;
.LBB0_516:
	s_add_u32 s14, s2, s8
	s_addc_u32 s15, s3, s9
	s_add_u32 s12, s14, 0x100
	s_addc_u32 s13, s15, 0
	s_and_b64 s[10:11], s[6:7], exec
	s_cselect_b32 s11, s3, s13
	s_cselect_b32 s10, s2, s12
	s_add_u32 s8, s0, s8
	s_addc_u32 s9, s1, s9
	s_add_u32 s8, s8, 0x100
	s_addc_u32 s9, s9, 0
	s_add_i32 s39, 0, 0x10000
	s_and_b64 s[6:7], s[6:7], exec
	s_cselect_b32 s13, s1, s9
	s_cselect_b32 s12, s0, s8
	s_add_i32 s7, 0, 0x14000
	s_add_u32 s16, s14, 0x40080
	s_addc_u32 s17, s15, 0
	s_add_i32 s38, s39, s21
	s_add_i32 m0, s22, 0xc000
	s_add_i32 s41, s22, 0xe000
	s_add_i32 s35, s38, 0x2000
	s_add_u32 s14, s12, 0x10000
	v_add_u32_e32 v150, s39, v136
	v_add_u32_e32 v158, s7, v136
	s_addc_u32 s15, s13, 0
	s_add_i32 s37, s7, s21
	ds_read_b128 v[138:141], v150
	ds_read_b128 v[142:145], v150 offset:1024
	ds_read_b128 v[146:149], v150 offset:2048
	ds_read_b128 v[150:153], v150 offset:3072
	ds_read_b128 v[154:157], v158
	ds_read_b128 v[162:165], v158 offset:1024
	ds_read_b128 v[168:171], v158 offset:2048
	ds_read_b128 v[172:175], v158 offset:3072
	s_add_i32 s36, s37, 0x2000
	s_add_i32 s34, 0, 0x18000
	s_add_i32 s31, 0, 0x1c000
	s_add_u32 s8, s10, 0x40000
	s_addc_u32 s9, s11, 0
	s_add_i32 s30, s34, s21
	s_add_i32 s29, s30, 0x2000
	s_add_u32 s6, s12, 0x10080
	s_addc_u32 s7, s13, 0
	s_add_i32 s40, s31, s21
	s_add_i32 s39, s40, 0x2000
	v_lshl_add_u64 v[158:159], s[16:17], 0, v[128:129]
	ds_read_b128 v[176:179], v137
	ds_read_b128 v[180:183], v137 offset:1024
	ds_read_b128 v[184:187], v137 offset:2048
	ds_read_b128 v[188:191], v137 offset:3072
	ds_read_b128 v[192:195], v137 offset:4096
	ds_read_b128 v[196:199], v137 offset:5120
	ds_read_b128 v[210:213], v137 offset:6144
	ds_read_b128 v[214:217], v137 offset:7168
	global_load_lds_dwordx4 v[158:159], off
	v_lshl_add_u64 v[158:159], s[16:17], 0, v[130:131]
	s_mov_b32 m0, s41
	s_nop 0
	global_load_lds_dwordx4 v[158:159], off
	s_waitcnt vmcnt(8)
	s_waitcnt lgkmcnt(0)
	s_barrier
	s_setprio 1
	v_mfma_f32_16x16x32_bf16 v[124:127], v[138:141], v[176:179], v[124:127]
	v_mfma_f32_16x16x32_bf16 v[120:123], v[146:149], v[176:179], v[120:123]
	v_mfma_f32_16x16x32_bf16 v[116:119], v[138:141], v[184:187], v[116:119]
	v_mfma_f32_16x16x32_bf16 v[112:115], v[146:149], v[184:187], v[112:115]
	v_mfma_f32_16x16x32_bf16 v[100:103], v[138:141], v[192:195], v[100:103]
	v_mfma_f32_16x16x32_bf16 v[96:99], v[146:149], v[192:195], v[96:99]
	v_mfma_f32_16x16x32_bf16 v[84:87], v[138:141], v[210:213], v[84:87]
	v_mfma_f32_16x16x32_bf16 v[80:83], v[146:149], v[210:213], v[80:83]
	v_mfma_f32_16x16x32_bf16 v[124:127], v[142:145], v[180:183], v[124:127]
	v_mfma_f32_16x16x32_bf16 v[120:123], v[150:153], v[180:183], v[120:123]
	v_mfma_f32_16x16x32_bf16 v[116:119], v[142:145], v[188:191], v[116:119]
	v_mfma_f32_16x16x32_bf16 v[112:115], v[150:153], v[188:191], v[112:115]
	v_mfma_f32_16x16x32_bf16 v[100:103], v[142:145], v[196:199], v[100:103]
	v_mfma_f32_16x16x32_bf16 v[96:99], v[150:153], v[196:199], v[96:99]
	v_mfma_f32_16x16x32_bf16 v[84:87], v[142:145], v[214:217], v[84:87]
	v_mfma_f32_16x16x32_bf16 v[80:83], v[150:153], v[214:217], v[80:83]
	v_mfma_f32_16x16x32_bf16 v[108:111], v[154:157], v[176:179], v[108:111]
	v_mfma_f32_16x16x32_bf16 v[104:107], v[168:171], v[176:179], v[104:107]
	v_mfma_f32_16x16x32_bf16 v[92:95], v[154:157], v[184:187], v[92:95]
	v_mfma_f32_16x16x32_bf16 v[88:91], v[168:171], v[184:187], v[88:91]
	v_mfma_f32_16x16x32_bf16 v[76:79], v[154:157], v[192:195], v[76:79]
	v_mfma_f32_16x16x32_bf16 v[72:75], v[168:171], v[192:195], v[72:75]
	v_mfma_f32_16x16x32_bf16 v[68:71], v[154:157], v[210:213], v[68:71]
	v_mfma_f32_16x16x32_bf16 v[64:67], v[168:171], v[210:213], v[64:67]
	v_mfma_f32_16x16x32_bf16 v[108:111], v[162:165], v[180:183], v[108:111]
	v_mfma_f32_16x16x32_bf16 v[104:107], v[172:175], v[180:183], v[104:107]
	v_mfma_f32_16x16x32_bf16 v[92:95], v[162:165], v[188:191], v[92:95]
	v_mfma_f32_16x16x32_bf16 v[88:91], v[172:175], v[188:191], v[88:91]
	v_mfma_f32_16x16x32_bf16 v[76:79], v[162:165], v[196:199], v[76:79]
	v_mfma_f32_16x16x32_bf16 v[72:75], v[172:175], v[196:199], v[72:75]
	v_mfma_f32_16x16x32_bf16 v[68:71], v[162:165], v[214:217], v[68:71]
	v_mfma_f32_16x16x32_bf16 v[64:67], v[172:175], v[214:217], v[64:67]
	s_setprio 0
	s_barrier
	s_mov_b32 m0, s38
	v_lshl_add_u64 v[158:159], s[12:13], 0, v[160:161]
	ds_read_b128 v[176:179], v137 offset:16384
	ds_read_b128 v[180:183], v137 offset:17408
	ds_read_b128 v[184:187], v137 offset:18432
	ds_read_b128 v[188:191], v137 offset:19456
	ds_read_b128 v[192:195], v137 offset:20480
	ds_read_b128 v[196:199], v137 offset:21504
	ds_read_b128 v[210:213], v137 offset:22528
	ds_read_b128 v[214:217], v137 offset:23552
	global_load_lds_dwordx4 v[158:159], off
	v_lshl_add_u64 v[218:219], s[12:13], 0, v[132:133]
	s_mov_b32 m0, s35
	v_lshl_add_u64 v[220:221], s[14:15], 0, v[160:161]
	global_load_lds_dwordx4 v[218:219], off
	s_mov_b32 m0, s37
	v_lshl_add_u64 v[222:223], s[10:11], 0, v[130:131]
	global_load_lds_dwordx4 v[220:221], off
	v_lshl_add_u64 v[220:221], s[14:15], 0, v[132:133]
	s_mov_b32 m0, s36
	s_nop 0
	global_load_lds_dwordx4 v[220:221], off
	v_lshl_add_u64 v[220:221], s[10:11], 0, v[128:129]
	s_mov_b32 m0, s22
	s_nop 0
	global_load_lds_dwordx4 v[220:221], off
	s_mov_b32 m0, s23
	s_nop 0
	global_load_lds_dwordx4 v[222:223], off
	s_waitcnt vmcnt(8)
	s_waitcnt lgkmcnt(0)
	s_barrier
; #define PG8_STAGE(bufoff, gbase, voff) do { _Pragma("unroll") for (int _i = 0; _i < 2; ++_i) \
;         __builtin_amdgcn_global_load_lds((const unsigned*)((const char*)(gbase) + (voff)[_i]), (LAS unsigned*)(lds + (bufoff) + ldsw + _i * 8192), 16, 0, 0); } while (0)
; #define PG8_LDA(dst, b, h) do { _Pragma("unroll") for (int m = 0; m < 4; ++m) _Pragma("unroll") for (int k = 0; k < 2; ++k) dst[m][k] = *(const LAS bf16x8*)(lds + PG8_SA(b, h) + aoff + m * 2048 + k * 1024); } while (0)
; #define PG8_LDB(dst, b, h) do { _Pragma("unroll") for (int n = 0; n < 2; ++n) _Pragma("unroll") for (int k = 0; k < 2; ++k) dst[n][k] = *(const LAS bf16x8*)(lds + PG8_SB(b, h) + boff + n * 2048 + k * 1024); } while (0)
; #define PG8_MMA(ai, bj, At, Bt) do { __builtin_amdgcn_s_setprio(1); _Pragma("unroll") for (int m = 0; m < 4; ++m) _Pragma("unroll") for (int n = 0; n < 2; ++n) _Pragma("unroll") for (int k = 0; k < 2; ++k) \
;         acc[ai][bj][m][n] = __builtin_amdgcn_mfma_f32_16x16x32_bf16(Bt[n][k], At[m][k], acc[ai][bj][m][n], 0, 0, 0); __builtin_amdgcn_s_setprio(0); } while (0)
; #define PG8_WAIT_V(n) asm volatile("s_waitcnt vmcnt(" #n ")" ::: "memory")
; #define PG8_WAIT_L(n) asm volatile("s_waitcnt lgkmcnt(" #n ")" ::: "memory")
; #define PG8_BAR __builtin_amdgcn_s_barrier()
; #define PG8_SCHED __builtin_amdgcn_sched_barrier(0)
; template <class Epi, class Sched>
; DI void gemm_phase(const int wv, LAS unsigned char* lds, const int lda, const int ldb, const int K, const Sched& S, const Epi& E) {
;     ...
;             PG8_WAIT_V(8); PG8_WAIT_L(0); PG8_BAR; PG8_MMA(1, 0, At, B0); PG8_MMA(1, 1, At, B1); PG8_BAR; PG8_SCHED;
;             PG8_LDB(B0, 1, 0); PG8_LDB(B1, 1, 1); PG8_SCHED; PG8_LDA(At, 1, 0); PG8_STAGE(PG8_SA(0, 1), a2 + hstepA, voffA);
;             PG8_WAIT_V(8); PG8_WAIT_L(0); PG8_BAR; PG8_MMA(0, 0, At, B0); PG8_MMA(0, 1, At, B1); PG8_BAR; PG8_SCHED;
	s_setprio 1
	v_mfma_f32_16x16x32_bf16 v[60:63], v[138:141], v[176:179], v[60:63]
	v_mfma_f32_16x16x32_bf16 v[56:59], v[146:149], v[176:179], v[56:59]
	v_mfma_f32_16x16x32_bf16 v[52:55], v[138:141], v[184:187], v[52:55]
	v_mfma_f32_16x16x32_bf16 v[48:51], v[146:149], v[184:187], v[48:51]
	v_mfma_f32_16x16x32_bf16 v[36:39], v[138:141], v[192:195], v[36:39]
	v_mfma_f32_16x16x32_bf16 v[32:35], v[146:149], v[192:195], v[32:35]
	v_mfma_f32_16x16x32_bf16 v[20:23], v[138:141], v[210:213], v[20:23]
	v_mfma_f32_16x16x32_bf16 v[16:19], v[146:149], v[210:213], v[16:19]
	v_mfma_f32_16x16x32_bf16 v[60:63], v[142:145], v[180:183], v[60:63]
	v_mfma_f32_16x16x32_bf16 v[56:59], v[150:153], v[180:183], v[56:59]
	v_mfma_f32_16x16x32_bf16 v[52:55], v[142:145], v[188:191], v[52:55]
	v_mfma_f32_16x16x32_bf16 v[48:51], v[150:153], v[188:191], v[48:51]
	v_mfma_f32_16x16x32_bf16 v[36:39], v[142:145], v[196:199], v[36:39]
	v_mfma_f32_16x16x32_bf16 v[32:35], v[150:153], v[196:199], v[32:35]
	v_mfma_f32_16x16x32_bf16 v[20:23], v[142:145], v[214:217], v[20:23]
	v_mfma_f32_16x16x32_bf16 v[16:19], v[150:153], v[214:217], v[16:19]
	v_mfma_f32_16x16x32_bf16 v[44:47], v[154:157], v[176:179], v[44:47]
	v_mfma_f32_16x16x32_bf16 v[40:43], v[168:171], v[176:179], v[40:43]
	v_mfma_f32_16x16x32_bf16 v[28:31], v[154:157], v[184:187], v[28:31]
	v_mfma_f32_16x16x32_bf16 v[24:27], v[168:171], v[184:187], v[24:27]
	v_mfma_f32_16x16x32_bf16 v[12:15], v[154:157], v[192:195], v[12:15]
	v_mfma_f32_16x16x32_bf16 v[8:11], v[168:171], v[192:195], v[8:11]
	v_mfma_f32_16x16x32_bf16 v[4:7], v[154:157], v[210:213], v[4:7]
	v_mfma_f32_16x16x32_bf16 v[0:3], v[168:171], v[210:213], v[0:3]
	v_mfma_f32_16x16x32_bf16 v[44:47], v[162:165], v[180:183], v[44:47]
	v_mfma_f32_16x16x32_bf16 v[40:43], v[172:175], v[180:183], v[40:43]
	v_mfma_f32_16x16x32_bf16 v[28:31], v[162:165], v[188:191], v[28:31]
	v_mfma_f32_16x16x32_bf16 v[24:27], v[172:175], v[188:191], v[24:27]
	v_mfma_f32_16x16x32_bf16 v[12:15], v[162:165], v[196:199], v[12:15]
	v_mfma_f32_16x16x32_bf16 v[8:11], v[172:175], v[196:199], v[8:11]
	v_mfma_f32_16x16x32_bf16 v[4:7], v[162:165], v[214:217], v[4:7]
	v_mfma_f32_16x16x32_bf16 v[0:3], v[172:175], v[214:217], v[0:3]
	s_setprio 0
	s_barrier
	v_add_u32_e32 v150, s34, v136
	v_add_u32_e32 v172, s31, v136
	ds_read_b128 v[138:141], v150
	ds_read_b128 v[142:145], v150 offset:1024
	ds_read_b128 v[146:149], v150 offset:2048
	ds_read_b128 v[150:153], v150 offset:3072
	ds_read_b128 v[154:157], v172
	ds_read_b128 v[162:165], v172 offset:1024
	ds_read_b128 v[168:171], v172 offset:2048
	ds_read_b128 v[172:175], v172 offset:3072
	s_mov_b32 m0, s24
	v_lshl_add_u64 v[224:225], s[8:9], 0, v[128:129]
	ds_read_b128 v[176:179], v137 offset:32768
	ds_read_b128 v[180:183], v137 offset:33792
	ds_read_b128 v[184:187], v137 offset:34816
	ds_read_b128 v[188:191], v137 offset:35840
	ds_read_b128 v[192:195], v137 offset:36864
	ds_read_b128 v[196:199], v137 offset:37888
	ds_read_b128 v[210:213], v137 offset:38912
	ds_read_b128 v[214:217], v137 offset:39936
	global_load_lds_dwordx4 v[224:225], off
	v_lshl_add_u64 v[224:225], s[8:9], 0, v[130:131]
	s_mov_b32 m0, s25
	s_nop 0
	global_load_lds_dwordx4 v[224:225], off
	s_waitcnt vmcnt(8)
	s_waitcnt lgkmcnt(0)
	s_barrier
	s_setprio 1
	v_mfma_f32_16x16x32_bf16 v[124:127], v[138:141], v[176:179], v[124:127]
	v_mfma_f32_16x16x32_bf16 v[120:123], v[146:149], v[176:179], v[120:123]
	v_mfma_f32_16x16x32_bf16 v[116:119], v[138:141], v[184:187], v[116:119]
	v_mfma_f32_16x16x32_bf16 v[112:115], v[146:149], v[184:187], v[112:115]
	v_mfma_f32_16x16x32_bf16 v[100:103], v[138:141], v[192:195], v[100:103]
	v_mfma_f32_16x16x32_bf16 v[96:99], v[146:149], v[192:195], v[96:99]
	v_mfma_f32_16x16x32_bf16 v[84:87], v[138:141], v[210:213], v[84:87]
	v_mfma_f32_16x16x32_bf16 v[80:83], v[146:149], v[210:213], v[80:83]
	v_mfma_f32_16x16x32_bf16 v[124:127], v[142:145], v[180:183], v[124:127]
	v_mfma_f32_16x16x32_bf16 v[120:123], v[150:153], v[180:183], v[120:123]
	v_mfma_f32_16x16x32_bf16 v[116:119], v[142:145], v[188:191], v[116:119]
	v_mfma_f32_16x16x32_bf16 v[112:115], v[150:153], v[188:191], v[112:115]
	v_mfma_f32_16x16x32_bf16 v[100:103], v[142:145], v[196:199], v[100:103]
	v_mfma_f32_16x16x32_bf16 v[96:99], v[150:153], v[196:199], v[96:99]
	v_mfma_f32_16x16x32_bf16 v[84:87], v[142:145], v[214:217], v[84:87]
	v_mfma_f32_16x16x32_bf16 v[80:83], v[150:153], v[214:217], v[80:83]
	v_mfma_f32_16x16x32_bf16 v[108:111], v[154:157], v[176:179], v[108:111]
	v_mfma_f32_16x16x32_bf16 v[104:107], v[168:171], v[176:179], v[104:107]
	v_mfma_f32_16x16x32_bf16 v[92:95], v[154:157], v[184:187], v[92:95]
	v_mfma_f32_16x16x32_bf16 v[88:91], v[168:171], v[184:187], v[88:91]
	v_mfma_f32_16x16x32_bf16 v[76:79], v[154:157], v[192:195], v[76:79]
	v_mfma_f32_16x16x32_bf16 v[72:75], v[168:171], v[192:195], v[72:75]
	v_mfma_f32_16x16x32_bf16 v[68:71], v[154:157], v[210:213], v[68:71]
	v_mfma_f32_16x16x32_bf16 v[64:67], v[168:171], v[210:213], v[64:67]
	v_mfma_f32_16x16x32_bf16 v[108:111], v[162:165], v[180:183], v[108:111]
	v_mfma_f32_16x16x32_bf16 v[104:107], v[172:175], v[180:183], v[104:107]
	v_mfma_f32_16x16x32_bf16 v[92:95], v[162:165], v[188:191], v[92:95]
	v_mfma_f32_16x16x32_bf16 v[88:91], v[172:175], v[188:191], v[88:91]
	v_mfma_f32_16x16x32_bf16 v[76:79], v[162:165], v[196:199], v[76:79]
	v_mfma_f32_16x16x32_bf16 v[72:75], v[172:175], v[196:199], v[72:75]
	v_mfma_f32_16x16x32_bf16 v[68:71], v[162:165], v[214:217], v[68:71]
	v_mfma_f32_16x16x32_bf16 v[64:67], v[172:175], v[214:217], v[64:67]
	s_setprio 0
	s_barrier
; #define PG8_STAGE(bufoff, gbase, voff) do { _Pragma("unroll") for (int _i = 0; _i < 2; ++_i) \
;         __builtin_amdgcn_global_load_lds((const unsigned*)((const char*)(gbase) + (voff)[_i]), (LAS unsigned*)(lds + (bufoff) + ldsw + _i * 8192), 16, 0, 0); } while (0)
; #define PG8_LDA(dst, b, h) do { _Pragma("unroll") for (int m = 0; m < 4; ++m) _Pragma("unroll") for (int k = 0; k < 2; ++k) dst[m][k] = *(const LAS bf16x8*)(lds + PG8_SA(b, h) + aoff + m * 2048 + k * 1024); } while (0)
; #define PG8_MMA(ai, bj, At, Bt) do { __builtin_amdgcn_s_setprio(1); _Pragma("unroll") for (int m = 0; m < 4; ++m) _Pragma("unroll") for (int n = 0; n < 2; ++n) _Pragma("unroll") for (int k = 0; k < 2; ++k) \
;         acc[ai][bj][m][n] = __builtin_amdgcn_mfma_f32_16x16x32_bf16(Bt[n][k], At[m][k], acc[ai][bj][m][n], 0, 0, 0); __builtin_amdgcn_s_setprio(0); } while (0)
; #define PG8_WAIT_V(n) asm volatile("s_waitcnt vmcnt(" #n ")" ::: "memory")
; #define PG8_WAIT_L(n) asm volatile("s_waitcnt lgkmcnt(" #n ")" ::: "memory")
; #define PG8_BAR __builtin_amdgcn_s_barrier()
; #define PG8_SCHED __builtin_amdgcn_sched_barrier(0)
; template <class Epi, class Sched>
; DI void gemm_phase(const int wv, LAS unsigned char* lds, const int lda, const int ldb, const int K, const Sched& S, const Epi& E) {
;     ...
;             PG8_LDA(At, 1, 1); PG8_STAGE(PG8_SB(1, 0), b3, voffB); PG8_STAGE(PG8_SB(1, 1), b3 + hstepB, voffB); PG8_STAGE(PG8_SA(1, 0), a3, voffA);
;             PG8_WAIT_V(8); PG8_WAIT_L(0); PG8_BAR; PG8_MMA(1, 0, At, B0); PG8_MMA(1, 1, At, B1); PG8_BAR; PG8_SCHED;
;         }
;         if (wr == 0) PG8_BAR;
	s_mov_b32 m0, s30
	v_lshl_add_u64 v[158:159], v[158:159], 0, s[78:79]
	ds_read_b128 v[176:179], v137 offset:49152
	ds_read_b128 v[180:183], v137 offset:50176
	ds_read_b128 v[184:187], v137 offset:51200
	ds_read_b128 v[188:191], v137 offset:52224
	ds_read_b128 v[192:195], v137 offset:53248
	ds_read_b128 v[196:199], v137 offset:54272
	ds_read_b128 v[210:213], v137 offset:55296
	ds_read_b128 v[214:217], v137 offset:56320
	global_load_lds_dwordx4 v[158:159], off
	v_lshl_add_u64 v[158:159], v[218:219], 0, s[78:79]
	s_mov_b32 m0, s29
	s_nop 0
	global_load_lds_dwordx4 v[158:159], off
	v_lshl_add_u64 v[158:159], s[6:7], 0, v[160:161]
	s_mov_b32 m0, s40
	s_nop 0
	global_load_lds_dwordx4 v[158:159], off
	v_lshl_add_u64 v[158:159], s[6:7], 0, v[132:133]
	s_mov_b32 m0, s39
	s_nop 0
	global_load_lds_dwordx4 v[158:159], off
	v_lshl_add_u64 v[158:159], v[220:221], 0, s[78:79]
	s_mov_b32 m0, s27
	s_nop 0
	global_load_lds_dwordx4 v[158:159], off
	v_lshl_add_u64 v[158:159], v[222:223], 0, s[78:79]
	s_mov_b32 m0, s28
	s_nop 0
	global_load_lds_dwordx4 v[158:159], off
	s_waitcnt vmcnt(8)
	s_waitcnt lgkmcnt(0)
	s_barrier
	s_setprio 1
	v_mfma_f32_16x16x32_bf16 v[60:63], v[138:141], v[176:179], v[60:63]
	v_mfma_f32_16x16x32_bf16 v[56:59], v[146:149], v[176:179], v[56:59]
	v_mfma_f32_16x16x32_bf16 v[52:55], v[138:141], v[184:187], v[52:55]
	v_mfma_f32_16x16x32_bf16 v[48:51], v[146:149], v[184:187], v[48:51]
	v_mfma_f32_16x16x32_bf16 v[36:39], v[138:141], v[192:195], v[36:39]
	v_mfma_f32_16x16x32_bf16 v[32:35], v[146:149], v[192:195], v[32:35]
	v_mfma_f32_16x16x32_bf16 v[20:23], v[138:141], v[210:213], v[20:23]
	v_mfma_f32_16x16x32_bf16 v[16:19], v[146:149], v[210:213], v[16:19]
	v_mfma_f32_16x16x32_bf16 v[60:63], v[142:145], v[180:183], v[60:63]
	v_mfma_f32_16x16x32_bf16 v[56:59], v[150:153], v[180:183], v[56:59]
	v_mfma_f32_16x16x32_bf16 v[52:55], v[142:145], v[188:191], v[52:55]
	v_mfma_f32_16x16x32_bf16 v[48:51], v[150:153], v[188:191], v[48:51]
	v_mfma_f32_16x16x32_bf16 v[36:39], v[142:145], v[196:199], v[36:39]
	v_mfma_f32_16x16x32_bf16 v[32:35], v[150:153], v[196:199], v[32:35]
	v_mfma_f32_16x16x32_bf16 v[20:23], v[142:145], v[214:217], v[20:23]
	v_mfma_f32_16x16x32_bf16 v[16:19], v[150:153], v[214:217], v[16:19]
	v_mfma_f32_16x16x32_bf16 v[44:47], v[154:157], v[176:179], v[44:47]
	v_mfma_f32_16x16x32_bf16 v[40:43], v[168:171], v[176:179], v[40:43]
	v_mfma_f32_16x16x32_bf16 v[28:31], v[154:157], v[184:187], v[28:31]
	v_mfma_f32_16x16x32_bf16 v[24:27], v[168:171], v[184:187], v[24:27]
	v_mfma_f32_16x16x32_bf16 v[12:15], v[154:157], v[192:195], v[12:15]
	v_mfma_f32_16x16x32_bf16 v[8:11], v[168:171], v[192:195], v[8:11]
	v_mfma_f32_16x16x32_bf16 v[4:7], v[154:157], v[210:213], v[4:7]
	v_mfma_f32_16x16x32_bf16 v[0:3], v[168:171], v[210:213], v[0:3]
	v_mfma_f32_16x16x32_bf16 v[44:47], v[162:165], v[180:183], v[44:47]
	v_mfma_f32_16x16x32_bf16 v[40:43], v[172:175], v[180:183], v[40:43]
	v_mfma_f32_16x16x32_bf16 v[28:31], v[162:165], v[188:191], v[28:31]
	v_mfma_f32_16x16x32_bf16 v[24:27], v[172:175], v[188:191], v[24:27]
	v_mfma_f32_16x16x32_bf16 v[12:15], v[162:165], v[196:199], v[12:15]
	v_mfma_f32_16x16x32_bf16 v[8:11], v[172:175], v[196:199], v[8:11]
	v_mfma_f32_16x16x32_bf16 v[4:7], v[162:165], v[214:217], v[4:7]
	v_mfma_f32_16x16x32_bf16 v[0:3], v[172:175], v[214:217], v[0:3]
	s_setprio 0
	s_barrier
	s_andn2_b64 vcc, exec, s[4:5]
	s_mov_b64 s[6:7], -1
	s_mov_b64 s[4:5], 0
	s_mov_b64 s[8:9], 0x100
	s_cbranch_vccz .LBB0_516
	s_cmpk_lt_u32 s20, 0x100
	s_cbranch_scc0 .LBB0_519
	s_barrier

; #define PG8_STAGE(bufoff, gbase, voff) do { _Pragma("unroll") for (int _i = 0; _i < 2; ++_i) \
;         __builtin_amdgcn_global_load_lds((const unsigned*)((const char*)(gbase) + (voff)[_i]), (LAS unsigned*)(lds + (bufoff) + ldsw + _i * 8192), 16, 0, 0); } while (0)
; #define PG8_LDA(dst, b, h) do { _Pragma("unroll") for (int m = 0; m < 4; ++m) _Pragma("unroll") for (int k = 0; k < 2; ++k) dst[m][k] = *(const LAS bf16x8*)(lds + PG8_SA(b, h) + aoff + m * 2048 + k * 1024); } while (0)
; #define PG8_LDB(dst, b, h) do { _Pragma("unroll") for (int n = 0; n < 2; ++n) _Pragma("unroll") for (int k = 0; k < 2; ++k) dst[n][k] = *(const LAS bf16x8*)(lds + PG8_SB(b, h) + boff + n * 2048 + k * 1024); } while (0)
; #define PG8_MMA(ai, bj, At, Bt) do { __builtin_amdgcn_s_setprio(1); _Pragma("unroll") for (int m = 0; m < 4; ++m) _Pragma("unroll") for (int n = 0; n < 2; ++n) _Pragma("unroll") for (int k = 0; k < 2; ++k) \
;         acc[ai][bj][m][n] = __builtin_amdgcn_mfma_f32_16x16x32_bf16(Bt[n][k], At[m][k], acc[ai][bj][m][n], 0, 0, 0); __builtin_amdgcn_s_setprio(0); } while (0)
; #define PG8_WAIT_V(n) asm volatile("s_waitcnt vmcnt(" #n ")" ::: "memory")
; #define PG8_WAIT_L(n) asm volatile("s_waitcnt lgkmcnt(" #n ")" ::: "memory")
; #define PG8_BAR __builtin_amdgcn_s_barrier()
; #define PG8_SCHED __builtin_amdgcn_sched_barrier(0)
; template <class Epi, class Sched>
; DI void gemm_phase(const int wv, LAS unsigned char* lds, const int lda, const int ldb, const int K, const Sched& S, const Epi& E) {
;     ...
;             const char* a1 = cA + (size_t)(t + 1) * kstep;
;             const char* a2 = last ? nA : cA + (size_t)(t + 2) * kstep; const char* b2 = last ? nB : cB + (size_t)(t + 2) * kstep;
;             const char* a3 = a2 + kstep; const char* b3 = b2 + kstep;
;             PG8_LDB(B0, 0, 0); PG8_LDB(B1, 0, 1); PG8_SCHED; PG8_LDA(At, 0, 0); PG8_STAGE(PG8_SA(1, 1), a1 + hstepA, voffA);
;             PG8_WAIT_V(8); PG8_WAIT_L(0); PG8_BAR; PG8_MMA(0, 0, At, B0); PG8_MMA(0, 1, At, B1); PG8_BAR; PG8_SCHED;
;             PG8_LDA(At, 0, 1); PG8_STAGE(PG8_SB(0, 0), b2, voffB); PG8_STAGE(PG8_SB(0, 1), b2 + hstepB, voffB); PG8_STAGE(PG8_SA(0, 0), a2, voffA);
;             PG8_WAIT_V(8); PG8_WAIT_L(0); PG8_BAR; PG8_MMA(1, 0, At, B0); PG8_MMA(1, 1, At, B1); PG8_BAR; PG8_SCHED;
.LBB0_686:
	s_add_u32 s18, s16, 0xfff80080
	s_addc_u32 s19, s17, -1
	s_add_i32 s42, 0, 0x10000
	s_cmp_eq_u32 s41, 28
	s_cselect_b32 s21, s13, s19
	s_cselect_b32 s20, s12, s18
	s_cselect_b32 s19, s15, s40
	s_cselect_b32 s18, s14, s11
	s_add_i32 s44, 0, 0x14000
	v_add_u32_e32 v140, s42, v157
	v_add_u32_e32 v154, s44, v157
	ds_read_b128 v[128:131], v140
	ds_read_b128 v[132:135], v140 offset:1024
	ds_read_b128 v[136:139], v140 offset:2048
	ds_read_b128 v[140:143], v140 offset:3072
	ds_read_b128 v[162:165], v154
	ds_read_b128 v[168:171], v154 offset:1024
	ds_read_b128 v[172:175], v154 offset:2048
	ds_read_b128 v[176:179], v154 offset:3072
	v_lshl_add_u64 v[154:155], s[16:17], 0, v[152:153]
	s_add_i32 m0, s27, 0xc000
	ds_read_b128 v[180:183], v159
	ds_read_b128 v[184:187], v159 offset:1024
	ds_read_b128 v[188:191], v159 offset:2048
	ds_read_b128 v[192:195], v159 offset:3072
	ds_read_b128 v[196:199], v159 offset:4096
	ds_read_b128 v[210:213], v159 offset:5120
	ds_read_b128 v[214:217], v159 offset:6144
	ds_read_b128 v[218:221], v159 offset:7168
	global_load_lds_dwordx4 v[154:155], off
	v_lshl_add_u64 v[154:155], s[16:17], 0, v[150:151]
	s_add_i32 m0, s27, 0xe000
	s_nop 0
	global_load_lds_dwordx4 v[154:155], off
	s_waitcnt vmcnt(8)
	s_waitcnt lgkmcnt(0)
	s_barrier
	s_setprio 1
	v_mfma_f32_16x16x32_bf16 v[124:127], v[128:131], v[180:183], v[124:127]
	v_mfma_f32_16x16x32_bf16 v[120:123], v[136:139], v[180:183], v[120:123]
	v_mfma_f32_16x16x32_bf16 v[116:119], v[128:131], v[188:191], v[116:119]
	v_mfma_f32_16x16x32_bf16 v[108:111], v[136:139], v[188:191], v[108:111]
	v_mfma_f32_16x16x32_bf16 v[100:103], v[128:131], v[196:199], v[100:103]
	v_mfma_f32_16x16x32_bf16 v[92:95], v[136:139], v[196:199], v[92:95]
	v_mfma_f32_16x16x32_bf16 v[84:87], v[128:131], v[214:217], v[84:87]
	v_mfma_f32_16x16x32_bf16 v[76:79], v[136:139], v[214:217], v[76:79]
	v_mfma_f32_16x16x32_bf16 v[124:127], v[132:135], v[184:187], v[124:127]
	v_mfma_f32_16x16x32_bf16 v[120:123], v[140:143], v[184:187], v[120:123]
	v_mfma_f32_16x16x32_bf16 v[116:119], v[132:135], v[192:195], v[116:119]
	v_mfma_f32_16x16x32_bf16 v[108:111], v[140:143], v[192:195], v[108:111]
	v_mfma_f32_16x16x32_bf16 v[100:103], v[132:135], v[210:213], v[100:103]
	v_mfma_f32_16x16x32_bf16 v[92:95], v[140:143], v[210:213], v[92:95]
	v_mfma_f32_16x16x32_bf16 v[84:87], v[132:135], v[218:221], v[84:87]
	v_mfma_f32_16x16x32_bf16 v[76:79], v[140:143], v[218:221], v[76:79]
	v_mfma_f32_16x16x32_bf16 v[112:115], v[162:165], v[180:183], v[112:115]
	v_mfma_f32_16x16x32_bf16 v[104:107], v[172:175], v[180:183], v[104:107]
	v_mfma_f32_16x16x32_bf16 v[96:99], v[162:165], v[188:191], v[96:99]
	v_mfma_f32_16x16x32_bf16 v[88:91], v[172:175], v[188:191], v[88:91]
	v_mfma_f32_16x16x32_bf16 v[80:83], v[162:165], v[196:199], v[80:83]
	v_mfma_f32_16x16x32_bf16 v[72:75], v[172:175], v[196:199], v[72:75]
	v_mfma_f32_16x16x32_bf16 v[68:71], v[162:165], v[214:217], v[68:71]
	v_mfma_f32_16x16x32_bf16 v[64:67], v[172:175], v[214:217], v[64:67]
	v_mfma_f32_16x16x32_bf16 v[112:115], v[168:171], v[184:187], v[112:115]
	v_mfma_f32_16x16x32_bf16 v[104:107], v[176:179], v[184:187], v[104:107]
	v_mfma_f32_16x16x32_bf16 v[96:99], v[168:171], v[192:195], v[96:99]
	v_mfma_f32_16x16x32_bf16 v[88:91], v[176:179], v[192:195], v[88:91]
	v_mfma_f32_16x16x32_bf16 v[80:83], v[168:171], v[210:213], v[80:83]
	v_mfma_f32_16x16x32_bf16 v[72:75], v[176:179], v[210:213], v[72:75]
	v_mfma_f32_16x16x32_bf16 v[68:71], v[168:171], v[218:221], v[68:71]
	v_mfma_f32_16x16x32_bf16 v[64:67], v[176:179], v[218:221], v[64:67]
	s_setprio 0
	s_barrier
	s_add_i32 s42, s42, s26
	v_lshl_add_u64 v[154:155], s[18:19], 0, v[160:161]
	s_mov_b32 m0, s42
	ds_read_b128 v[180:183], v159 offset:16384
	ds_read_b128 v[184:187], v159 offset:17408
	ds_read_b128 v[188:191], v159 offset:18432
	ds_read_b128 v[192:195], v159 offset:19456
	ds_read_b128 v[196:199], v159 offset:20480
	ds_read_b128 v[210:213], v159 offset:21504
	ds_read_b128 v[214:217], v159 offset:22528
	ds_read_b128 v[218:221], v159 offset:23552
	global_load_lds_dwordx4 v[154:155], off
	s_add_i32 m0, s42, 0x2000
	s_add_u32 s42, s18, 0x80000
	v_lshl_add_u64 v[222:223], s[18:19], 0, v[144:145]
	s_addc_u32 s43, s19, 0
	s_add_i32 s44, s44, s26
	global_load_lds_dwordx4 v[222:223], off
	v_lshl_add_u64 v[224:225], s[42:43], 0, v[160:161]
	s_mov_b32 m0, s44
	v_lshl_add_u64 v[226:227], s[20:21], 0, v[146:147]
	global_load_lds_dwordx4 v[224:225], off
	v_lshl_add_u64 v[224:225], s[42:43], 0, v[144:145]
	s_add_i32 m0, s44, 0x2000
	s_nop 0
	global_load_lds_dwordx4 v[224:225], off
	v_lshl_add_u64 v[224:225], s[20:21], 0, v[148:149]
	s_mov_b32 m0, s27
	s_nop 0
	global_load_lds_dwordx4 v[224:225], off
	s_mov_b32 m0, s28
	s_nop 0
	global_load_lds_dwordx4 v[226:227], off
	s_waitcnt vmcnt(8)
	s_waitcnt lgkmcnt(0)
	s_barrier
; #define PG8_STAGE(bufoff, gbase, voff) do { _Pragma("unroll") for (int _i = 0; _i < 2; ++_i) \
;         __builtin_amdgcn_global_load_lds((const unsigned*)((const char*)(gbase) + (voff)[_i]), (LAS unsigned*)(lds + (bufoff) + ldsw + _i * 8192), 16, 0, 0); } while (0)
; #define PG8_LDA(dst, b, h) do { _Pragma("unroll") for (int m = 0; m < 4; ++m) _Pragma("unroll") for (int k = 0; k < 2; ++k) dst[m][k] = *(const LAS bf16x8*)(lds + PG8_SA(b, h) + aoff + m * 2048 + k * 1024); } while (0)
; #define PG8_LDB(dst, b, h) do { _Pragma("unroll") for (int n = 0; n < 2; ++n) _Pragma("unroll") for (int k = 0; k < 2; ++k) dst[n][k] = *(const LAS bf16x8*)(lds + PG8_SB(b, h) + boff + n * 2048 + k * 1024); } while (0)
; #define PG8_MMA(ai, bj, At, Bt) do { __builtin_amdgcn_s_setprio(1); _Pragma("unroll") for (int m = 0; m < 4; ++m) _Pragma("unroll") for (int n = 0; n < 2; ++n) _Pragma("unroll") for (int k = 0; k < 2; ++k) \
;         acc[ai][bj][m][n] = __builtin_amdgcn_mfma_f32_16x16x32_bf16(Bt[n][k], At[m][k], acc[ai][bj][m][n], 0, 0, 0); __builtin_amdgcn_s_setprio(0); } while (0)
; #define PG8_WAIT_V(n) asm volatile("s_waitcnt vmcnt(" #n ")" ::: "memory")
; #define PG8_WAIT_L(n) asm volatile("s_waitcnt lgkmcnt(" #n ")" ::: "memory")
; #define PG8_BAR __builtin_amdgcn_s_barrier()
; #define PG8_SCHED __builtin_amdgcn_sched_barrier(0)
; template <class Epi, class Sched>
; DI void gemm_phase(const int wv, LAS unsigned char* lds, const int lda, const int ldb, const int K, const Sched& S, const Epi& E) {
;     ...
;             PG8_WAIT_V(8); PG8_WAIT_L(0); PG8_BAR; PG8_MMA(1, 0, At, B0); PG8_MMA(1, 1, At, B1); PG8_BAR; PG8_SCHED;
;             PG8_LDB(B0, 1, 0); PG8_LDB(B1, 1, 1); PG8_SCHED; PG8_LDA(At, 1, 0); PG8_STAGE(PG8_SA(0, 1), a2 + hstepA, voffA);
;             PG8_WAIT_V(8); PG8_WAIT_L(0); PG8_BAR; PG8_MMA(0, 0, At, B0); PG8_MMA(0, 1, At, B1); PG8_BAR; PG8_SCHED;
	s_setprio 1
	v_mfma_f32_16x16x32_bf16 v[60:63], v[128:131], v[180:183], v[60:63]
	v_mfma_f32_16x16x32_bf16 v[56:59], v[136:139], v[180:183], v[56:59]
	v_mfma_f32_16x16x32_bf16 v[52:55], v[128:131], v[188:191], v[52:55]
	v_mfma_f32_16x16x32_bf16 v[44:47], v[136:139], v[188:191], v[44:47]
	v_mfma_f32_16x16x32_bf16 v[36:39], v[128:131], v[196:199], v[36:39]
	v_mfma_f32_16x16x32_bf16 v[28:31], v[136:139], v[196:199], v[28:31]
	v_mfma_f32_16x16x32_bf16 v[20:23], v[128:131], v[214:217], v[20:23]
	v_mfma_f32_16x16x32_bf16 v[12:15], v[136:139], v[214:217], v[12:15]
	v_mfma_f32_16x16x32_bf16 v[60:63], v[132:135], v[184:187], v[60:63]
	v_mfma_f32_16x16x32_bf16 v[56:59], v[140:143], v[184:187], v[56:59]
	v_mfma_f32_16x16x32_bf16 v[52:55], v[132:135], v[192:195], v[52:55]
	v_mfma_f32_16x16x32_bf16 v[44:47], v[140:143], v[192:195], v[44:47]
	v_mfma_f32_16x16x32_bf16 v[36:39], v[132:135], v[210:213], v[36:39]
	v_mfma_f32_16x16x32_bf16 v[28:31], v[140:143], v[210:213], v[28:31]
	v_mfma_f32_16x16x32_bf16 v[20:23], v[132:135], v[218:221], v[20:23]
	v_mfma_f32_16x16x32_bf16 v[12:15], v[140:143], v[218:221], v[12:15]
	v_mfma_f32_16x16x32_bf16 v[48:51], v[162:165], v[180:183], v[48:51]
	v_mfma_f32_16x16x32_bf16 v[40:43], v[172:175], v[180:183], v[40:43]
	v_mfma_f32_16x16x32_bf16 v[32:35], v[162:165], v[188:191], v[32:35]
	v_mfma_f32_16x16x32_bf16 v[24:27], v[172:175], v[188:191], v[24:27]
	v_mfma_f32_16x16x32_bf16 v[16:19], v[162:165], v[196:199], v[16:19]
	v_mfma_f32_16x16x32_bf16 v[8:11], v[172:175], v[196:199], v[8:11]
	v_mfma_f32_16x16x32_bf16 v[4:7], v[162:165], v[214:217], v[4:7]
	v_mfma_f32_16x16x32_bf16 v[0:3], v[172:175], v[214:217], v[0:3]
	v_mfma_f32_16x16x32_bf16 v[48:51], v[168:171], v[184:187], v[48:51]
	v_mfma_f32_16x16x32_bf16 v[40:43], v[176:179], v[184:187], v[40:43]
	v_mfma_f32_16x16x32_bf16 v[32:35], v[168:171], v[192:195], v[32:35]
	v_mfma_f32_16x16x32_bf16 v[24:27], v[176:179], v[192:195], v[24:27]
	v_mfma_f32_16x16x32_bf16 v[16:19], v[168:171], v[210:213], v[16:19]
	v_mfma_f32_16x16x32_bf16 v[8:11], v[176:179], v[210:213], v[8:11]
	v_mfma_f32_16x16x32_bf16 v[4:7], v[168:171], v[218:221], v[4:7]
	v_mfma_f32_16x16x32_bf16 v[0:3], v[176:179], v[218:221], v[0:3]
	s_setprio 0
	s_barrier
	s_add_i32 s42, 0, 0x18000
	s_add_i32 s43, 0, 0x1c000
	v_add_u32_e32 v140, s42, v157
	v_add_u32_e32 v176, s43, v157
	ds_read_b128 v[128:131], v140
	ds_read_b128 v[132:135], v140 offset:1024
	ds_read_b128 v[136:139], v140 offset:2048
	ds_read_b128 v[140:143], v140 offset:3072
	ds_read_b128 v[162:165], v176
	ds_read_b128 v[168:171], v176 offset:1024
	ds_read_b128 v[172:175], v176 offset:2048
	ds_read_b128 v[176:179], v176 offset:3072
	s_add_u32 s20, s20, 0x80000
	s_addc_u32 s21, s21, 0
	s_mov_b32 m0, s29
	v_lshl_add_u64 v[228:229], s[20:21], 0, v[148:149]
	ds_read_b128 v[180:183], v159 offset:32768
	ds_read_b128 v[184:187], v159 offset:33792
	ds_read_b128 v[188:191], v159 offset:34816
	ds_read_b128 v[192:195], v159 offset:35840
	ds_read_b128 v[196:199], v159 offset:36864
	ds_read_b128 v[210:213], v159 offset:37888
	ds_read_b128 v[214:217], v159 offset:38912
	ds_read_b128 v[218:221], v159 offset:39936
	global_load_lds_dwordx4 v[228:229], off
	v_lshl_add_u64 v[228:229], s[20:21], 0, v[146:147]
	s_mov_b32 m0, s30
	s_nop 0
	global_load_lds_dwordx4 v[228:229], off
	s_waitcnt vmcnt(8)
	s_waitcnt lgkmcnt(0)
	s_barrier
	s_setprio 1
	v_mfma_f32_16x16x32_bf16 v[124:127], v[128:131], v[180:183], v[124:127]
	v_mfma_f32_16x16x32_bf16 v[120:123], v[136:139], v[180:183], v[120:123]
	v_mfma_f32_16x16x32_bf16 v[116:119], v[128:131], v[188:191], v[116:119]
	v_mfma_f32_16x16x32_bf16 v[108:111], v[136:139], v[188:191], v[108:111]
	v_mfma_f32_16x16x32_bf16 v[100:103], v[128:131], v[196:199], v[100:103]
	v_mfma_f32_16x16x32_bf16 v[92:95], v[136:139], v[196:199], v[92:95]
	v_mfma_f32_16x16x32_bf16 v[84:87], v[128:131], v[214:217], v[84:87]
	v_mfma_f32_16x16x32_bf16 v[76:79], v[136:139], v[214:217], v[76:79]
	v_mfma_f32_16x16x32_bf16 v[124:127], v[132:135], v[184:187], v[124:127]
	v_mfma_f32_16x16x32_bf16 v[120:123], v[140:143], v[184:187], v[120:123]
	v_mfma_f32_16x16x32_bf16 v[116:119], v[132:135], v[192:195], v[116:119]
	v_mfma_f32_16x16x32_bf16 v[108:111], v[140:143], v[192:195], v[108:111]
	v_mfma_f32_16x16x32_bf16 v[100:103], v[132:135], v[210:213], v[100:103]
	v_mfma_f32_16x16x32_bf16 v[92:95], v[140:143], v[210:213], v[92:95]
	v_mfma_f32_16x16x32_bf16 v[84:87], v[132:135], v[218:221], v[84:87]
	v_mfma_f32_16x16x32_bf16 v[76:79], v[140:143], v[218:221], v[76:79]
	v_mfma_f32_16x16x32_bf16 v[112:115], v[162:165], v[180:183], v[112:115]
	v_mfma_f32_16x16x32_bf16 v[104:107], v[172:175], v[180:183], v[104:107]
	v_mfma_f32_16x16x32_bf16 v[96:99], v[162:165], v[188:191], v[96:99]
	v_mfma_f32_16x16x32_bf16 v[88:91], v[172:175], v[188:191], v[88:91]
	v_mfma_f32_16x16x32_bf16 v[80:83], v[162:165], v[196:199], v[80:83]
	v_mfma_f32_16x16x32_bf16 v[72:75], v[172:175], v[196:199], v[72:75]
	v_mfma_f32_16x16x32_bf16 v[68:71], v[162:165], v[214:217], v[68:71]
	v_mfma_f32_16x16x32_bf16 v[64:67], v[172:175], v[214:217], v[64:67]
	v_mfma_f32_16x16x32_bf16 v[112:115], v[168:171], v[184:187], v[112:115]
	v_mfma_f32_16x16x32_bf16 v[104:107], v[176:179], v[184:187], v[104:107]
	v_mfma_f32_16x16x32_bf16 v[96:99], v[168:171], v[192:195], v[96:99]
	v_mfma_f32_16x16x32_bf16 v[88:91], v[176:179], v[192:195], v[88:91]
	v_mfma_f32_16x16x32_bf16 v[80:83], v[168:171], v[210:213], v[80:83]
	v_mfma_f32_16x16x32_bf16 v[72:75], v[176:179], v[210:213], v[72:75]
	v_mfma_f32_16x16x32_bf16 v[68:71], v[168:171], v[218:221], v[68:71]
	v_mfma_f32_16x16x32_bf16 v[64:67], v[176:179], v[218:221], v[64:67]
	s_setprio 0
	s_barrier
; #define PG8_STAGE(bufoff, gbase, voff) do { _Pragma("unroll") for (int _i = 0; _i < 2; ++_i) \
;         __builtin_amdgcn_global_load_lds((const unsigned*)((const char*)(gbase) + (voff)[_i]), (LAS unsigned*)(lds + (bufoff) + ldsw + _i * 8192), 16, 0, 0); } while (0)
; #define PG8_LDA(dst, b, h) do { _Pragma("unroll") for (int m = 0; m < 4; ++m) _Pragma("unroll") for (int k = 0; k < 2; ++k) dst[m][k] = *(const LAS bf16x8*)(lds + PG8_SA(b, h) + aoff + m * 2048 + k * 1024); } while (0)
; #define PG8_MMA(ai, bj, At, Bt) do { __builtin_amdgcn_s_setprio(1); _Pragma("unroll") for (int m = 0; m < 4; ++m) _Pragma("unroll") for (int n = 0; n < 2; ++n) _Pragma("unroll") for (int k = 0; k < 2; ++k) \
;         acc[ai][bj][m][n] = __builtin_amdgcn_mfma_f32_16x16x32_bf16(Bt[n][k], At[m][k], acc[ai][bj][m][n], 0, 0, 0); __builtin_amdgcn_s_setprio(0); } while (0)
; #define PG8_WAIT_V(n) asm volatile("s_waitcnt vmcnt(" #n ")" ::: "memory")
; #define PG8_WAIT_L(n) asm volatile("s_waitcnt lgkmcnt(" #n ")" ::: "memory")
; #define PG8_BAR __builtin_amdgcn_s_barrier()
; #define PG8_SCHED __builtin_amdgcn_sched_barrier(0)
; template <class Epi, class Sched>
; DI void gemm_phase(const int wv, LAS unsigned char* lds, const int lda, const int ldb, const int K, const Sched& S, const Epi& E) {
;     ...
;             PG8_LDA(At, 1, 1); PG8_STAGE(PG8_SB(1, 0), b3, voffB); PG8_STAGE(PG8_SB(1, 1), b3 + hstepB, voffB); PG8_STAGE(PG8_SA(1, 0), a3, voffA);
;             PG8_WAIT_V(8); PG8_WAIT_L(0); PG8_BAR; PG8_MMA(1, 0, At, B0); PG8_MMA(1, 1, At, B1); PG8_BAR; PG8_SCHED;
;         }
;         if (wr == 0) PG8_BAR;
	s_add_i32 s20, s42, s26
	v_lshl_add_u64 v[154:155], v[154:155], 0, s[78:79]
	s_mov_b32 m0, s20
	ds_read_b128 v[180:183], v159 offset:49152
	ds_read_b128 v[184:187], v159 offset:50176
	ds_read_b128 v[188:191], v159 offset:51200
	ds_read_b128 v[192:195], v159 offset:52224
	ds_read_b128 v[196:199], v159 offset:53248
	ds_read_b128 v[210:213], v159 offset:54272
	ds_read_b128 v[214:217], v159 offset:55296
	ds_read_b128 v[218:221], v159 offset:56320
	global_load_lds_dwordx4 v[154:155], off
	s_add_i32 m0, s20, 0x2000
	s_add_u32 s18, s18, 0x80080
	v_lshl_add_u64 v[154:155], v[222:223], 0, s[78:79]
	s_addc_u32 s19, s19, 0
	s_add_i32 s20, s43, s26
	global_load_lds_dwordx4 v[154:155], off
	v_lshl_add_u64 v[154:155], s[18:19], 0, v[160:161]
	s_mov_b32 m0, s20
	s_nop 0
	global_load_lds_dwordx4 v[154:155], off
	v_lshl_add_u64 v[154:155], s[18:19], 0, v[144:145]
	s_add_i32 m0, s20, 0x2000
	s_nop 0
	global_load_lds_dwordx4 v[154:155], off
	v_lshl_add_u64 v[154:155], v[224:225], 0, s[78:79]
	s_mov_b32 m0, s35
	s_nop 0
	global_load_lds_dwordx4 v[154:155], off
	v_lshl_add_u64 v[154:155], v[226:227], 0, s[78:79]
	s_mov_b32 m0, s36
	s_nop 0
	global_load_lds_dwordx4 v[154:155], off
	s_waitcnt vmcnt(8)
	s_waitcnt lgkmcnt(0)
	s_barrier
	s_setprio 1
	v_mfma_f32_16x16x32_bf16 v[60:63], v[128:131], v[180:183], v[60:63]
	v_mfma_f32_16x16x32_bf16 v[56:59], v[136:139], v[180:183], v[56:59]
	v_mfma_f32_16x16x32_bf16 v[52:55], v[128:131], v[188:191], v[52:55]
	v_mfma_f32_16x16x32_bf16 v[44:47], v[136:139], v[188:191], v[44:47]
	v_mfma_f32_16x16x32_bf16 v[36:39], v[128:131], v[196:199], v[36:39]
	v_mfma_f32_16x16x32_bf16 v[28:31], v[136:139], v[196:199], v[28:31]
	v_mfma_f32_16x16x32_bf16 v[20:23], v[128:131], v[214:217], v[20:23]
	v_mfma_f32_16x16x32_bf16 v[12:15], v[136:139], v[214:217], v[12:15]
	v_mfma_f32_16x16x32_bf16 v[60:63], v[132:135], v[184:187], v[60:63]
	v_mfma_f32_16x16x32_bf16 v[56:59], v[140:143], v[184:187], v[56:59]
	v_mfma_f32_16x16x32_bf16 v[52:55], v[132:135], v[192:195], v[52:55]
	v_mfma_f32_16x16x32_bf16 v[44:47], v[140:143], v[192:195], v[44:47]
	v_mfma_f32_16x16x32_bf16 v[36:39], v[132:135], v[210:213], v[36:39]
	v_mfma_f32_16x16x32_bf16 v[28:31], v[140:143], v[210:213], v[28:31]
	v_mfma_f32_16x16x32_bf16 v[20:23], v[132:135], v[218:221], v[20:23]
	v_mfma_f32_16x16x32_bf16 v[12:15], v[140:143], v[218:221], v[12:15]
	v_mfma_f32_16x16x32_bf16 v[48:51], v[162:165], v[180:183], v[48:51]
	v_mfma_f32_16x16x32_bf16 v[40:43], v[172:175], v[180:183], v[40:43]
	v_mfma_f32_16x16x32_bf16 v[32:35], v[162:165], v[188:191], v[32:35]
	v_mfma_f32_16x16x32_bf16 v[24:27], v[172:175], v[188:191], v[24:27]
	v_mfma_f32_16x16x32_bf16 v[16:19], v[162:165], v[196:199], v[16:19]
	v_mfma_f32_16x16x32_bf16 v[8:11], v[172:175], v[196:199], v[8:11]
	v_mfma_f32_16x16x32_bf16 v[4:7], v[162:165], v[214:217], v[4:7]
	v_mfma_f32_16x16x32_bf16 v[0:3], v[172:175], v[214:217], v[0:3]
	v_mfma_f32_16x16x32_bf16 v[48:51], v[168:171], v[184:187], v[48:51]
	v_mfma_f32_16x16x32_bf16 v[40:43], v[176:179], v[184:187], v[40:43]
	v_mfma_f32_16x16x32_bf16 v[32:35], v[168:171], v[192:195], v[32:35]
	v_mfma_f32_16x16x32_bf16 v[24:27], v[176:179], v[192:195], v[24:27]
	v_mfma_f32_16x16x32_bf16 v[16:19], v[168:171], v[210:213], v[16:19]
	v_mfma_f32_16x16x32_bf16 v[8:11], v[176:179], v[210:213], v[8:11]
	v_mfma_f32_16x16x32_bf16 v[4:7], v[168:171], v[218:221], v[4:7]
	v_mfma_f32_16x16x32_bf16 v[0:3], v[176:179], v[218:221], v[0:3]
	s_setprio 0
	s_barrier
	s_add_i32 s41, s41, 2
	s_add_u32 s11, s11, 0x100
	s_addc_u32 s40, s40, 0
	s_add_u32 s16, s16, 0x100
	s_addc_u32 s17, s17, 0
	s_cmp_gt_u32 s41, 29
	s_cbranch_scc0 .LBB0_686
	s_and_b64 vcc, exec, s[8:9]
	s_cbranch_vccz .LBB0_689
	s_barrier

; #define PG8_STAGE(bufoff, gbase, voff) do { _Pragma("unroll") for (int _i = 0; _i < 2; ++_i) \
;         __builtin_amdgcn_global_load_lds((const unsigned*)((const char*)(gbase) + (voff)[_i]), (LAS unsigned*)(lds + (bufoff) + ldsw + _i * 8192), 16, 0, 0); } while (0)
; #define PG8_LDA(dst, b, h) do { _Pragma("unroll") for (int m = 0; m < 4; ++m) _Pragma("unroll") for (int k = 0; k < 2; ++k) dst[m][k] = *(const LAS bf16x8*)(lds + PG8_SA(b, h) + aoff + m * 2048 + k * 1024); } while (0)
; #define PG8_LDB(dst, b, h) do { _Pragma("unroll") for (int n = 0; n < 2; ++n) _Pragma("unroll") for (int k = 0; k < 2; ++k) dst[n][k] = *(const LAS bf16x8*)(lds + PG8_SB(b, h) + boff + n * 2048 + k * 1024); } while (0)
; #define PG8_MMA(ai, bj, At, Bt) do { __builtin_amdgcn_s_setprio(1); _Pragma("unroll") for (int m = 0; m < 4; ++m) _Pragma("unroll") for (int n = 0; n < 2; ++n) _Pragma("unroll") for (int k = 0; k < 2; ++k) \
;         acc[ai][bj][m][n] = __builtin_amdgcn_mfma_f32_16x16x32_bf16(Bt[n][k], At[m][k], acc[ai][bj][m][n], 0, 0, 0); __builtin_amdgcn_s_setprio(0); } while (0)
; #define PG8_WAIT_V(n) asm volatile("s_waitcnt vmcnt(" #n ")" ::: "memory")
; #define PG8_WAIT_L(n) asm volatile("s_waitcnt lgkmcnt(" #n ")" ::: "memory")
; #define PG8_BAR __builtin_amdgcn_s_barrier()
; #define PG8_SCHED __builtin_amdgcn_sched_barrier(0)
; template <class Epi, class Sched>
; DI void gemm_phase(const int wv, LAS unsigned char* lds, const int lda, const int ldb, const int K, const Sched& S, const Epi& E) {
;     ...
;             const char* a1 = cA + (size_t)(t + 1) * kstep;
;             const char* a2 = last ? nA : cA + (size_t)(t + 2) * kstep; const char* b2 = last ? nB : cB + (size_t)(t + 2) * kstep;
;             const char* a3 = a2 + kstep; const char* b3 = b2 + kstep;
;             PG8_LDB(B0, 0, 0); PG8_LDB(B1, 0, 1); PG8_SCHED; PG8_LDA(At, 0, 0); PG8_STAGE(PG8_SA(1, 1), a1 + hstepA, voffA);
;             PG8_WAIT_V(8); PG8_WAIT_L(0); PG8_BAR; PG8_MMA(0, 0, At, B0); PG8_MMA(0, 1, At, B1); PG8_BAR; PG8_SCHED;
;             PG8_LDA(At, 0, 1); PG8_STAGE(PG8_SB(0, 0), b2, voffB); PG8_STAGE(PG8_SB(0, 1), b2 + hstepB, voffB); PG8_STAGE(PG8_SA(0, 0), a2, voffA);
;             PG8_WAIT_V(8); PG8_WAIT_L(0); PG8_BAR; PG8_MMA(1, 0, At, B0); PG8_MMA(1, 1, At, B1); PG8_BAR; PG8_SCHED;
.LBB0_825:
	s_add_u32 s20, s18, 0xfff80080
	s_addc_u32 s21, s19, -1
	s_add_i32 s42, 0, 0x10000
	s_cmp_eq_u32 s41, 28
	s_cselect_b32 s23, s15, s21
	s_cselect_b32 s22, s14, s20
	s_cselect_b32 s21, s17, s40
	s_cselect_b32 s20, s16, s13
	s_add_i32 s44, 0, 0x14000
	v_add_u32_e32 v154, s42, v139
	v_add_u32_e32 v158, s44, v139
	ds_read_b128 v[142:145], v154
	ds_read_b128 v[146:149], v154 offset:1024
	ds_read_b128 v[150:153], v154 offset:2048
	ds_read_b128 v[154:157], v154 offset:3072
	ds_read_b128 v[162:165], v158
	ds_read_b128 v[168:171], v158 offset:1024
	ds_read_b128 v[172:175], v158 offset:2048
	ds_read_b128 v[176:179], v158 offset:3072
	v_lshl_add_u64 v[158:159], s[18:19], 0, v[136:137]
	s_add_i32 m0, s29, 0xc000
	ds_read_b128 v[180:183], v141
	ds_read_b128 v[184:187], v141 offset:1024
	ds_read_b128 v[188:191], v141 offset:2048
	ds_read_b128 v[192:195], v141 offset:3072
	ds_read_b128 v[196:199], v141 offset:4096
	ds_read_b128 v[210:213], v141 offset:5120
	ds_read_b128 v[214:217], v141 offset:6144
	ds_read_b128 v[218:221], v141 offset:7168
	global_load_lds_dwordx4 v[158:159], off
	v_lshl_add_u64 v[158:159], s[18:19], 0, v[134:135]
	s_add_i32 m0, s29, 0xe000
	s_nop 0
	global_load_lds_dwordx4 v[158:159], off
	s_waitcnt vmcnt(8)
	s_waitcnt lgkmcnt(0)
	s_barrier
	s_setprio 1
	v_mfma_f32_16x16x32_bf16 v[124:127], v[142:145], v[180:183], v[124:127]
	v_mfma_f32_16x16x32_bf16 v[120:123], v[150:153], v[180:183], v[120:123]
	v_mfma_f32_16x16x32_bf16 v[108:111], v[142:145], v[188:191], v[108:111]
	v_mfma_f32_16x16x32_bf16 v[104:107], v[150:153], v[188:191], v[104:107]
	v_mfma_f32_16x16x32_bf16 v[92:95], v[142:145], v[196:199], v[92:95]
	v_mfma_f32_16x16x32_bf16 v[88:91], v[150:153], v[196:199], v[88:91]
	v_mfma_f32_16x16x32_bf16 v[76:79], v[142:145], v[214:217], v[76:79]
	v_mfma_f32_16x16x32_bf16 v[72:75], v[150:153], v[214:217], v[72:75]
	v_mfma_f32_16x16x32_bf16 v[124:127], v[146:149], v[184:187], v[124:127]
	v_mfma_f32_16x16x32_bf16 v[120:123], v[154:157], v[184:187], v[120:123]
	v_mfma_f32_16x16x32_bf16 v[108:111], v[146:149], v[192:195], v[108:111]
	v_mfma_f32_16x16x32_bf16 v[104:107], v[154:157], v[192:195], v[104:107]
	v_mfma_f32_16x16x32_bf16 v[92:95], v[146:149], v[210:213], v[92:95]
	v_mfma_f32_16x16x32_bf16 v[88:91], v[154:157], v[210:213], v[88:91]
	v_mfma_f32_16x16x32_bf16 v[76:79], v[146:149], v[218:221], v[76:79]
	v_mfma_f32_16x16x32_bf16 v[72:75], v[154:157], v[218:221], v[72:75]
	v_mfma_f32_16x16x32_bf16 v[116:119], v[162:165], v[180:183], v[116:119]
	v_mfma_f32_16x16x32_bf16 v[112:115], v[172:175], v[180:183], v[112:115]
	v_mfma_f32_16x16x32_bf16 v[100:103], v[162:165], v[188:191], v[100:103]
	v_mfma_f32_16x16x32_bf16 v[96:99], v[172:175], v[188:191], v[96:99]
	v_mfma_f32_16x16x32_bf16 v[84:87], v[162:165], v[196:199], v[84:87]
	v_mfma_f32_16x16x32_bf16 v[80:83], v[172:175], v[196:199], v[80:83]
	v_mfma_f32_16x16x32_bf16 v[68:71], v[162:165], v[214:217], v[68:71]
	v_mfma_f32_16x16x32_bf16 v[64:67], v[172:175], v[214:217], v[64:67]
	v_mfma_f32_16x16x32_bf16 v[116:119], v[168:171], v[184:187], v[116:119]
	v_mfma_f32_16x16x32_bf16 v[112:115], v[176:179], v[184:187], v[112:115]
	v_mfma_f32_16x16x32_bf16 v[100:103], v[168:171], v[192:195], v[100:103]
	v_mfma_f32_16x16x32_bf16 v[96:99], v[176:179], v[192:195], v[96:99]
	v_mfma_f32_16x16x32_bf16 v[84:87], v[168:171], v[210:213], v[84:87]
	v_mfma_f32_16x16x32_bf16 v[80:83], v[176:179], v[210:213], v[80:83]
	v_mfma_f32_16x16x32_bf16 v[68:71], v[168:171], v[218:221], v[68:71]
	v_mfma_f32_16x16x32_bf16 v[64:67], v[176:179], v[218:221], v[64:67]
	s_setprio 0
	s_barrier
	s_add_i32 s42, s42, s28
	v_lshl_add_u64 v[158:159], s[20:21], 0, v[160:161]
	s_mov_b32 m0, s42
	ds_read_b128 v[180:183], v141 offset:16384
	ds_read_b128 v[184:187], v141 offset:17408
	ds_read_b128 v[188:191], v141 offset:18432
	ds_read_b128 v[192:195], v141 offset:19456
	ds_read_b128 v[196:199], v141 offset:20480
	ds_read_b128 v[210:213], v141 offset:21504
	ds_read_b128 v[214:217], v141 offset:22528
	ds_read_b128 v[218:221], v141 offset:23552
	global_load_lds_dwordx4 v[158:159], off
	s_add_i32 m0, s42, 0x2000
	s_add_u32 s42, s20, 0x80000
	v_lshl_add_u64 v[222:223], s[20:21], 0, v[128:129]
	s_addc_u32 s43, s21, 0
	s_add_i32 s44, s44, s28
	global_load_lds_dwordx4 v[222:223], off
	v_lshl_add_u64 v[224:225], s[42:43], 0, v[160:161]
	s_mov_b32 m0, s44
	v_lshl_add_u64 v[226:227], s[22:23], 0, v[130:131]
	global_load_lds_dwordx4 v[224:225], off
	v_lshl_add_u64 v[224:225], s[42:43], 0, v[128:129]
	s_add_i32 m0, s44, 0x2000
	s_nop 0
	global_load_lds_dwordx4 v[224:225], off
	v_lshl_add_u64 v[224:225], s[22:23], 0, v[132:133]
	s_mov_b32 m0, s29
	s_nop 0
	global_load_lds_dwordx4 v[224:225], off
	s_mov_b32 m0, s30
	s_nop 0
	global_load_lds_dwordx4 v[226:227], off
	s_waitcnt vmcnt(8)
	s_waitcnt lgkmcnt(0)
	s_barrier
; #define PG8_STAGE(bufoff, gbase, voff) do { _Pragma("unroll") for (int _i = 0; _i < 2; ++_i) \
;         __builtin_amdgcn_global_load_lds((const unsigned*)((const char*)(gbase) + (voff)[_i]), (LAS unsigned*)(lds + (bufoff) + ldsw + _i * 8192), 16, 0, 0); } while (0)
; #define PG8_LDA(dst, b, h) do { _Pragma("unroll") for (int m = 0; m < 4; ++m) _Pragma("unroll") for (int k = 0; k < 2; ++k) dst[m][k] = *(const LAS bf16x8*)(lds + PG8_SA(b, h) + aoff + m * 2048 + k * 1024); } while (0)
; #define PG8_LDB(dst, b, h) do { _Pragma("unroll") for (int n = 0; n < 2; ++n) _Pragma("unroll") for (int k = 0; k < 2; ++k) dst[n][k] = *(const LAS bf16x8*)(lds + PG8_SB(b, h) + boff + n * 2048 + k * 1024); } while (0)
; #define PG8_MMA(ai, bj, At, Bt) do { __builtin_amdgcn_s_setprio(1); _Pragma("unroll") for (int m = 0; m < 4; ++m) _Pragma("unroll") for (int n = 0; n < 2; ++n) _Pragma("unroll") for (int k = 0; k < 2; ++k) \
;         acc[ai][bj][m][n] = __builtin_amdgcn_mfma_f32_16x16x32_bf16(Bt[n][k], At[m][k], acc[ai][bj][m][n], 0, 0, 0); __builtin_amdgcn_s_setprio(0); } while (0)
; #define PG8_WAIT_V(n) asm volatile("s_waitcnt vmcnt(" #n ")" ::: "memory")
; #define PG8_WAIT_L(n) asm volatile("s_waitcnt lgkmcnt(" #n ")" ::: "memory")
; #define PG8_BAR __builtin_amdgcn_s_barrier()
; #define PG8_SCHED __builtin_amdgcn_sched_barrier(0)
; template <class Epi, class Sched>
; DI void gemm_phase(const int wv, LAS unsigned char* lds, const int lda, const int ldb, const int K, const Sched& S, const Epi& E) {
;     ...
;             PG8_WAIT_V(8); PG8_WAIT_L(0); PG8_BAR; PG8_MMA(1, 0, At, B0); PG8_MMA(1, 1, At, B1); PG8_BAR; PG8_SCHED;
;             PG8_LDB(B0, 1, 0); PG8_LDB(B1, 1, 1); PG8_SCHED; PG8_LDA(At, 1, 0); PG8_STAGE(PG8_SA(0, 1), a2 + hstepA, voffA);
;             PG8_WAIT_V(8); PG8_WAIT_L(0); PG8_BAR; PG8_MMA(0, 0, At, B0); PG8_MMA(0, 1, At, B1); PG8_BAR; PG8_SCHED;
	s_setprio 1
	v_mfma_f32_16x16x32_bf16 v[60:63], v[142:145], v[180:183], v[60:63]
	v_mfma_f32_16x16x32_bf16 v[56:59], v[150:153], v[180:183], v[56:59]
	v_mfma_f32_16x16x32_bf16 v[44:47], v[142:145], v[188:191], v[44:47]
	v_mfma_f32_16x16x32_bf16 v[40:43], v[150:153], v[188:191], v[40:43]
	v_mfma_f32_16x16x32_bf16 v[28:31], v[142:145], v[196:199], v[28:31]
	v_mfma_f32_16x16x32_bf16 v[24:27], v[150:153], v[196:199], v[24:27]
	v_mfma_f32_16x16x32_bf16 v[12:15], v[142:145], v[214:217], v[12:15]
	v_mfma_f32_16x16x32_bf16 v[8:11], v[150:153], v[214:217], v[8:11]
	v_mfma_f32_16x16x32_bf16 v[60:63], v[146:149], v[184:187], v[60:63]
	v_mfma_f32_16x16x32_bf16 v[56:59], v[154:157], v[184:187], v[56:59]
	v_mfma_f32_16x16x32_bf16 v[44:47], v[146:149], v[192:195], v[44:47]
	v_mfma_f32_16x16x32_bf16 v[40:43], v[154:157], v[192:195], v[40:43]
	v_mfma_f32_16x16x32_bf16 v[28:31], v[146:149], v[210:213], v[28:31]
	v_mfma_f32_16x16x32_bf16 v[24:27], v[154:157], v[210:213], v[24:27]
	v_mfma_f32_16x16x32_bf16 v[12:15], v[146:149], v[218:221], v[12:15]
	v_mfma_f32_16x16x32_bf16 v[8:11], v[154:157], v[218:221], v[8:11]
	v_mfma_f32_16x16x32_bf16 v[52:55], v[162:165], v[180:183], v[52:55]
	v_mfma_f32_16x16x32_bf16 v[48:51], v[172:175], v[180:183], v[48:51]
	v_mfma_f32_16x16x32_bf16 v[36:39], v[162:165], v[188:191], v[36:39]
	v_mfma_f32_16x16x32_bf16 v[32:35], v[172:175], v[188:191], v[32:35]
	v_mfma_f32_16x16x32_bf16 v[20:23], v[162:165], v[196:199], v[20:23]
	v_mfma_f32_16x16x32_bf16 v[16:19], v[172:175], v[196:199], v[16:19]
	v_mfma_f32_16x16x32_bf16 v[4:7], v[162:165], v[214:217], v[4:7]
	v_mfma_f32_16x16x32_bf16 v[0:3], v[172:175], v[214:217], v[0:3]
	v_mfma_f32_16x16x32_bf16 v[52:55], v[168:171], v[184:187], v[52:55]
	v_mfma_f32_16x16x32_bf16 v[48:51], v[176:179], v[184:187], v[48:51]
	v_mfma_f32_16x16x32_bf16 v[36:39], v[168:171], v[192:195], v[36:39]
	v_mfma_f32_16x16x32_bf16 v[32:35], v[176:179], v[192:195], v[32:35]
	v_mfma_f32_16x16x32_bf16 v[20:23], v[168:171], v[210:213], v[20:23]
	v_mfma_f32_16x16x32_bf16 v[16:19], v[176:179], v[210:213], v[16:19]
	v_mfma_f32_16x16x32_bf16 v[4:7], v[168:171], v[218:221], v[4:7]
	v_mfma_f32_16x16x32_bf16 v[0:3], v[176:179], v[218:221], v[0:3]
	s_setprio 0
	s_barrier
	s_add_i32 s42, 0, 0x18000
	s_add_i32 s43, 0, 0x1c000
	v_add_u32_e32 v154, s42, v139
	v_add_u32_e32 v176, s43, v139
	ds_read_b128 v[142:145], v154
	ds_read_b128 v[146:149], v154 offset:1024
	ds_read_b128 v[150:153], v154 offset:2048
	ds_read_b128 v[154:157], v154 offset:3072
	ds_read_b128 v[162:165], v176
	ds_read_b128 v[168:171], v176 offset:1024
	ds_read_b128 v[172:175], v176 offset:2048
	ds_read_b128 v[176:179], v176 offset:3072
	s_add_u32 s22, s22, 0x80000
	s_addc_u32 s23, s23, 0
	s_mov_b32 m0, s31
	v_lshl_add_u64 v[228:229], s[22:23], 0, v[132:133]
	ds_read_b128 v[180:183], v141 offset:32768
	ds_read_b128 v[184:187], v141 offset:33792
	ds_read_b128 v[188:191], v141 offset:34816
	ds_read_b128 v[192:195], v141 offset:35840
	ds_read_b128 v[196:199], v141 offset:36864
	ds_read_b128 v[210:213], v141 offset:37888
	ds_read_b128 v[214:217], v141 offset:38912
	ds_read_b128 v[218:221], v141 offset:39936
	global_load_lds_dwordx4 v[228:229], off
	v_lshl_add_u64 v[228:229], s[22:23], 0, v[130:131]
	s_mov_b32 m0, s34
	s_nop 0
	global_load_lds_dwordx4 v[228:229], off
	s_waitcnt vmcnt(8)
	s_waitcnt lgkmcnt(0)
	s_barrier
	s_setprio 1
	v_mfma_f32_16x16x32_bf16 v[124:127], v[142:145], v[180:183], v[124:127]
	v_mfma_f32_16x16x32_bf16 v[120:123], v[150:153], v[180:183], v[120:123]
	v_mfma_f32_16x16x32_bf16 v[108:111], v[142:145], v[188:191], v[108:111]
	v_mfma_f32_16x16x32_bf16 v[104:107], v[150:153], v[188:191], v[104:107]
	v_mfma_f32_16x16x32_bf16 v[92:95], v[142:145], v[196:199], v[92:95]
	v_mfma_f32_16x16x32_bf16 v[88:91], v[150:153], v[196:199], v[88:91]
	v_mfma_f32_16x16x32_bf16 v[76:79], v[142:145], v[214:217], v[76:79]
	v_mfma_f32_16x16x32_bf16 v[72:75], v[150:153], v[214:217], v[72:75]
	v_mfma_f32_16x16x32_bf16 v[124:127], v[146:149], v[184:187], v[124:127]
	v_mfma_f32_16x16x32_bf16 v[120:123], v[154:157], v[184:187], v[120:123]
	v_mfma_f32_16x16x32_bf16 v[108:111], v[146:149], v[192:195], v[108:111]
	v_mfma_f32_16x16x32_bf16 v[104:107], v[154:157], v[192:195], v[104:107]
	v_mfma_f32_16x16x32_bf16 v[92:95], v[146:149], v[210:213], v[92:95]
	v_mfma_f32_16x16x32_bf16 v[88:91], v[154:157], v[210:213], v[88:91]
	v_mfma_f32_16x16x32_bf16 v[76:79], v[146:149], v[218:221], v[76:79]
	v_mfma_f32_16x16x32_bf16 v[72:75], v[154:157], v[218:221], v[72:75]
	v_mfma_f32_16x16x32_bf16 v[116:119], v[162:165], v[180:183], v[116:119]
	v_mfma_f32_16x16x32_bf16 v[112:115], v[172:175], v[180:183], v[112:115]
	v_mfma_f32_16x16x32_bf16 v[100:103], v[162:165], v[188:191], v[100:103]
	v_mfma_f32_16x16x32_bf16 v[96:99], v[172:175], v[188:191], v[96:99]
	v_mfma_f32_16x16x32_bf16 v[84:87], v[162:165], v[196:199], v[84:87]
	v_mfma_f32_16x16x32_bf16 v[80:83], v[172:175], v[196:199], v[80:83]
	v_mfma_f32_16x16x32_bf16 v[68:71], v[162:165], v[214:217], v[68:71]
	v_mfma_f32_16x16x32_bf16 v[64:67], v[172:175], v[214:217], v[64:67]
	v_mfma_f32_16x16x32_bf16 v[116:119], v[168:171], v[184:187], v[116:119]
	v_mfma_f32_16x16x32_bf16 v[112:115], v[176:179], v[184:187], v[112:115]
	v_mfma_f32_16x16x32_bf16 v[100:103], v[168:171], v[192:195], v[100:103]
	v_mfma_f32_16x16x32_bf16 v[96:99], v[176:179], v[192:195], v[96:99]
	v_mfma_f32_16x16x32_bf16 v[84:87], v[168:171], v[210:213], v[84:87]
	v_mfma_f32_16x16x32_bf16 v[80:83], v[176:179], v[210:213], v[80:83]
	v_mfma_f32_16x16x32_bf16 v[68:71], v[168:171], v[218:221], v[68:71]
	v_mfma_f32_16x16x32_bf16 v[64:67], v[176:179], v[218:221], v[64:67]
	s_setprio 0
	s_barrier
; #define PG8_STAGE(bufoff, gbase, voff) do { _Pragma("unroll") for (int _i = 0; _i < 2; ++_i) \
;         __builtin_amdgcn_global_load_lds((const unsigned*)((const char*)(gbase) + (voff)[_i]), (LAS unsigned*)(lds + (bufoff) + ldsw + _i * 8192), 16, 0, 0); } while (0)
; #define PG8_LDA(dst, b, h) do { _Pragma("unroll") for (int m = 0; m < 4; ++m) _Pragma("unroll") for (int k = 0; k < 2; ++k) dst[m][k] = *(const LAS bf16x8*)(lds + PG8_SA(b, h) + aoff + m * 2048 + k * 1024); } while (0)
; #define PG8_MMA(ai, bj, At, Bt) do { __builtin_amdgcn_s_setprio(1); _Pragma("unroll") for (int m = 0; m < 4; ++m) _Pragma("unroll") for (int n = 0; n < 2; ++n) _Pragma("unroll") for (int k = 0; k < 2; ++k) \
;         acc[ai][bj][m][n] = __builtin_amdgcn_mfma_f32_16x16x32_bf16(Bt[n][k], At[m][k], acc[ai][bj][m][n], 0, 0, 0); __builtin_amdgcn_s_setprio(0); } while (0)
; #define PG8_WAIT_V(n) asm volatile("s_waitcnt vmcnt(" #n ")" ::: "memory")
; #define PG8_WAIT_L(n) asm volatile("s_waitcnt lgkmcnt(" #n ")" ::: "memory")
; #define PG8_BAR __builtin_amdgcn_s_barrier()
; #define PG8_SCHED __builtin_amdgcn_sched_barrier(0)
; template <class Epi, class Sched>
; DI void gemm_phase(const int wv, LAS unsigned char* lds, const int lda, const int ldb, const int K, const Sched& S, const Epi& E) {
;     ...
;             PG8_LDA(At, 1, 1); PG8_STAGE(PG8_SB(1, 0), b3, voffB); PG8_STAGE(PG8_SB(1, 1), b3 + hstepB, voffB); PG8_STAGE(PG8_SA(1, 0), a3, voffA);
;             PG8_WAIT_V(8); PG8_WAIT_L(0); PG8_BAR; PG8_MMA(1, 0, At, B0); PG8_MMA(1, 1, At, B1); PG8_BAR; PG8_SCHED;
;         }
;         if (wr == 0) PG8_BAR;
	s_add_i32 s22, s42, s28
	v_lshl_add_u64 v[158:159], v[158:159], 0, s[78:79]
	s_mov_b32 m0, s22
	ds_read_b128 v[180:183], v141 offset:49152
	ds_read_b128 v[184:187], v141 offset:50176
	ds_read_b128 v[188:191], v141 offset:51200
	ds_read_b128 v[192:195], v141 offset:52224
	ds_read_b128 v[196:199], v141 offset:53248
	ds_read_b128 v[210:213], v141 offset:54272
	ds_read_b128 v[214:217], v141 offset:55296
	ds_read_b128 v[218:221], v141 offset:56320
	global_load_lds_dwordx4 v[158:159], off
	s_add_i32 m0, s22, 0x2000
	s_add_u32 s20, s20, 0x80080
	v_lshl_add_u64 v[158:159], v[222:223], 0, s[78:79]
	s_addc_u32 s21, s21, 0
	s_add_i32 s22, s43, s28
	global_load_lds_dwordx4 v[158:159], off
	v_lshl_add_u64 v[158:159], s[20:21], 0, v[160:161]
	s_mov_b32 m0, s22
	s_nop 0
	global_load_lds_dwordx4 v[158:159], off
	v_lshl_add_u64 v[158:159], s[20:21], 0, v[128:129]
	s_add_i32 m0, s22, 0x2000
	s_nop 0
	global_load_lds_dwordx4 v[158:159], off
	v_lshl_add_u64 v[158:159], v[224:225], 0, s[78:79]
	s_mov_b32 m0, s35
	s_nop 0
	global_load_lds_dwordx4 v[158:159], off
	v_lshl_add_u64 v[158:159], v[226:227], 0, s[78:79]
	s_mov_b32 m0, s36
	s_nop 0
	global_load_lds_dwordx4 v[158:159], off
	s_waitcnt vmcnt(8)
	s_waitcnt lgkmcnt(0)
	s_barrier
	s_setprio 1
	v_mfma_f32_16x16x32_bf16 v[60:63], v[142:145], v[180:183], v[60:63]
	v_mfma_f32_16x16x32_bf16 v[56:59], v[150:153], v[180:183], v[56:59]
	v_mfma_f32_16x16x32_bf16 v[44:47], v[142:145], v[188:191], v[44:47]
	v_mfma_f32_16x16x32_bf16 v[40:43], v[150:153], v[188:191], v[40:43]
	v_mfma_f32_16x16x32_bf16 v[28:31], v[142:145], v[196:199], v[28:31]
	v_mfma_f32_16x16x32_bf16 v[24:27], v[150:153], v[196:199], v[24:27]
	v_mfma_f32_16x16x32_bf16 v[12:15], v[142:145], v[214:217], v[12:15]
	v_mfma_f32_16x16x32_bf16 v[8:11], v[150:153], v[214:217], v[8:11]
	v_mfma_f32_16x16x32_bf16 v[60:63], v[146:149], v[184:187], v[60:63]
	v_mfma_f32_16x16x32_bf16 v[56:59], v[154:157], v[184:187], v[56:59]
	v_mfma_f32_16x16x32_bf16 v[44:47], v[146:149], v[192:195], v[44:47]
	v_mfma_f32_16x16x32_bf16 v[40:43], v[154:157], v[192:195], v[40:43]
	v_mfma_f32_16x16x32_bf16 v[28:31], v[146:149], v[210:213], v[28:31]
	v_mfma_f32_16x16x32_bf16 v[24:27], v[154:157], v[210:213], v[24:27]
	v_mfma_f32_16x16x32_bf16 v[12:15], v[146:149], v[218:221], v[12:15]
	v_mfma_f32_16x16x32_bf16 v[8:11], v[154:157], v[218:221], v[8:11]
	v_mfma_f32_16x16x32_bf16 v[52:55], v[162:165], v[180:183], v[52:55]
	v_mfma_f32_16x16x32_bf16 v[48:51], v[172:175], v[180:183], v[48:51]
	v_mfma_f32_16x16x32_bf16 v[36:39], v[162:165], v[188:191], v[36:39]
	v_mfma_f32_16x16x32_bf16 v[32:35], v[172:175], v[188:191], v[32:35]
	v_mfma_f32_16x16x32_bf16 v[20:23], v[162:165], v[196:199], v[20:23]
	v_mfma_f32_16x16x32_bf16 v[16:19], v[172:175], v[196:199], v[16:19]
	v_mfma_f32_16x16x32_bf16 v[4:7], v[162:165], v[214:217], v[4:7]
	v_mfma_f32_16x16x32_bf16 v[0:3], v[172:175], v[214:217], v[0:3]
	v_mfma_f32_16x16x32_bf16 v[52:55], v[168:171], v[184:187], v[52:55]
	v_mfma_f32_16x16x32_bf16 v[48:51], v[176:179], v[184:187], v[48:51]
	v_mfma_f32_16x16x32_bf16 v[36:39], v[168:171], v[192:195], v[36:39]
	v_mfma_f32_16x16x32_bf16 v[32:35], v[176:179], v[192:195], v[32:35]
	v_mfma_f32_16x16x32_bf16 v[20:23], v[168:171], v[210:213], v[20:23]
	v_mfma_f32_16x16x32_bf16 v[16:19], v[176:179], v[210:213], v[16:19]
	v_mfma_f32_16x16x32_bf16 v[4:7], v[168:171], v[218:221], v[4:7]
	v_mfma_f32_16x16x32_bf16 v[0:3], v[176:179], v[218:221], v[0:3]
	s_setprio 0
	s_barrier
	s_add_i32 s41, s41, 2
	s_add_u32 s13, s13, 0x100
	s_addc_u32 s40, s40, 0
	s_add_u32 s18, s18, 0x100
	s_addc_u32 s19, s19, 0
	s_cmp_gt_u32 s41, 29
	s_cbranch_scc0 .LBB0_825
	s_and_b64 vcc, exec, s[10:11]
	s_cbranch_vccz .LBB0_828
	s_barrier

; #define PG8_STAGE(bufoff, gbase, voff) do { _Pragma("unroll") for (int _i = 0; _i < 2; ++_i) \
;         __builtin_amdgcn_global_load_lds((const unsigned*)((const char*)(gbase) + (voff)[_i]), (LAS unsigned*)(lds + (bufoff) + ldsw + _i * 8192), 16, 0, 0); } while (0)
; #define PG8_LDA(dst, b, h) do { _Pragma("unroll") for (int m = 0; m < 4; ++m) _Pragma("unroll") for (int k = 0; k < 2; ++k) dst[m][k] = *(const LAS bf16x8*)(lds + PG8_SA(b, h) + aoff + m * 2048 + k * 1024); } while (0)
; #define PG8_LDB(dst, b, h) do { _Pragma("unroll") for (int n = 0; n < 2; ++n) _Pragma("unroll") for (int k = 0; k < 2; ++k) dst[n][k] = *(const LAS bf16x8*)(lds + PG8_SB(b, h) + boff + n * 2048 + k * 1024); } while (0)
; #define PG8_MMA(ai, bj, At, Bt) do { __builtin_amdgcn_s_setprio(1); _Pragma("unroll") for (int m = 0; m < 4; ++m) _Pragma("unroll") for (int n = 0; n < 2; ++n) _Pragma("unroll") for (int k = 0; k < 2; ++k) \
;         acc[ai][bj][m][n] = __builtin_amdgcn_mfma_f32_16x16x32_bf16(Bt[n][k], At[m][k], acc[ai][bj][m][n], 0, 0, 0); __builtin_amdgcn_s_setprio(0); } while (0)
; #define PG8_WAIT_V(n) asm volatile("s_waitcnt vmcnt(" #n ")" ::: "memory")
; #define PG8_WAIT_L(n) asm volatile("s_waitcnt lgkmcnt(" #n ")" ::: "memory")
; #define PG8_BAR __builtin_amdgcn_s_barrier()
; #define PG8_SCHED __builtin_amdgcn_sched_barrier(0)
; template <class Epi, class Sched>
; DI void gemm_phase(const int wv, LAS unsigned char* lds, const int lda, const int ldb, const int K, const Sched& S, const Epi& E) {
;     ...
;             const bool last = (t == nt - 2);
;             const char* a1 = cA + (size_t)(t + 1) * kstep;
;             const char* a2 = last ? nA : cA + (size_t)(t + 2) * kstep; const char* b2 = last ? nB : cB + (size_t)(t + 2) * kstep;
;             const char* a3 = a2 + kstep; const char* b3 = b2 + kstep;
;             PG8_LDB(B0, 0, 0); PG8_LDB(B1, 0, 1); PG8_SCHED; PG8_LDA(At, 0, 0); PG8_STAGE(PG8_SA(1, 1), a1 + hstepA, voffA);
;             PG8_WAIT_V(8); PG8_WAIT_L(0); PG8_BAR; PG8_MMA(0, 0, At, B0); PG8_MMA(0, 1, At, B1); PG8_BAR; PG8_SCHED;
;             PG8_LDA(At, 0, 1); PG8_STAGE(PG8_SB(0, 0), b2, voffB); PG8_STAGE(PG8_SB(0, 1), b2 + hstepB, voffB); PG8_STAGE(PG8_SA(0, 0), a2, voffA);
.LBB0_906:
	s_add_u32 s14, s12, 0xffea0080
	s_addc_u32 s15, s13, -1
	s_add_i32 s40, 0, 0x10000
	s_cmpk_eq_i32 s39, 0x54
	s_cselect_b32 s17, s9, s15
	s_cselect_b32 s16, s8, s14
	s_cselect_b32 s15, s11, s38
	s_cselect_b32 s14, s10, s37
	s_add_i32 s42, 0, 0x14000
	v_add_u32_e32 v76, s40, v157
	v_add_u32_e32 v154, s42, v157
	ds_read_b128 v[48:51], v76
	ds_read_b128 v[52:55], v76 offset:1024
	ds_read_b128 v[72:75], v76 offset:2048
	ds_read_b128 v[76:79], v76 offset:3072
	ds_read_b128 v[162:165], v154
	ds_read_b128 v[168:171], v154 offset:1024
	ds_read_b128 v[172:175], v154 offset:2048
	ds_read_b128 v[176:179], v154 offset:3072
	v_lshl_add_u64 v[154:155], s[12:13], 0, v[152:153]
	s_add_i32 m0, s23, 0xc000
	ds_read_b128 v[180:183], v159
	ds_read_b128 v[184:187], v159 offset:1024
	ds_read_b128 v[188:191], v159 offset:2048
	ds_read_b128 v[192:195], v159 offset:3072
	ds_read_b128 v[196:199], v159 offset:4096
	ds_read_b128 v[210:213], v159 offset:5120
	ds_read_b128 v[214:217], v159 offset:6144
	ds_read_b128 v[218:221], v159 offset:7168
	global_load_lds_dwordx4 v[154:155], off
	v_lshl_add_u64 v[154:155], s[12:13], 0, v[150:151]
	s_add_i32 m0, s23, 0xe000
	s_nop 0
	global_load_lds_dwordx4 v[154:155], off
	s_waitcnt vmcnt(8)
	s_waitcnt lgkmcnt(0)
	s_barrier
	s_setprio 1
	v_mfma_f32_16x16x32_bf16 v[140:143], v[48:51], v[180:183], v[140:143]
	v_mfma_f32_16x16x32_bf16 v[136:139], v[72:75], v[180:183], v[136:139]
	v_mfma_f32_16x16x32_bf16 v[124:127], v[48:51], v[188:191], v[124:127]
	v_mfma_f32_16x16x32_bf16 v[120:123], v[72:75], v[188:191], v[120:123]
	v_mfma_f32_16x16x32_bf16 v[116:119], v[48:51], v[196:199], v[116:119]
	v_mfma_f32_16x16x32_bf16 v[112:115], v[72:75], v[196:199], v[112:115]
	v_mfma_f32_16x16x32_bf16 v[100:103], v[48:51], v[214:217], v[100:103]
	v_mfma_f32_16x16x32_bf16 v[96:99], v[72:75], v[214:217], v[96:99]
	v_mfma_f32_16x16x32_bf16 v[140:143], v[52:55], v[184:187], v[140:143]
	v_mfma_f32_16x16x32_bf16 v[136:139], v[76:79], v[184:187], v[136:139]
	v_mfma_f32_16x16x32_bf16 v[124:127], v[52:55], v[192:195], v[124:127]
	v_mfma_f32_16x16x32_bf16 v[120:123], v[76:79], v[192:195], v[120:123]
	v_mfma_f32_16x16x32_bf16 v[116:119], v[52:55], v[210:213], v[116:119]
	v_mfma_f32_16x16x32_bf16 v[112:115], v[76:79], v[210:213], v[112:115]
	v_mfma_f32_16x16x32_bf16 v[100:103], v[52:55], v[218:221], v[100:103]
	v_mfma_f32_16x16x32_bf16 v[96:99], v[76:79], v[218:221], v[96:99]
	v_mfma_f32_16x16x32_bf16 v[132:135], v[162:165], v[180:183], v[132:135]
	v_mfma_f32_16x16x32_bf16 v[128:131], v[172:175], v[180:183], v[128:131]
	v_mfma_f32_16x16x32_bf16 v[108:111], v[162:165], v[188:191], v[108:111]
	v_mfma_f32_16x16x32_bf16 v[104:107], v[172:175], v[188:191], v[104:107]
	v_mfma_f32_16x16x32_bf16 v[92:95], v[162:165], v[196:199], v[92:95]
	v_mfma_f32_16x16x32_bf16 v[88:91], v[172:175], v[196:199], v[88:91]
	v_mfma_f32_16x16x32_bf16 v[84:87], v[162:165], v[214:217], v[84:87]
	v_mfma_f32_16x16x32_bf16 v[80:83], v[172:175], v[214:217], v[80:83]
	v_mfma_f32_16x16x32_bf16 v[132:135], v[168:171], v[184:187], v[132:135]
	v_mfma_f32_16x16x32_bf16 v[128:131], v[176:179], v[184:187], v[128:131]
	v_mfma_f32_16x16x32_bf16 v[108:111], v[168:171], v[192:195], v[108:111]
	v_mfma_f32_16x16x32_bf16 v[104:107], v[176:179], v[192:195], v[104:107]
	v_mfma_f32_16x16x32_bf16 v[92:95], v[168:171], v[210:213], v[92:95]
	v_mfma_f32_16x16x32_bf16 v[88:91], v[176:179], v[210:213], v[88:91]
	v_mfma_f32_16x16x32_bf16 v[84:87], v[168:171], v[218:221], v[84:87]
	v_mfma_f32_16x16x32_bf16 v[80:83], v[176:179], v[218:221], v[80:83]
	s_setprio 0
	s_barrier
	s_add_i32 s40, s40, s22
	v_lshl_add_u64 v[154:155], s[14:15], 0, v[160:161]
	s_mov_b32 m0, s40
	ds_read_b128 v[180:183], v159 offset:16384
	ds_read_b128 v[184:187], v159 offset:17408
	ds_read_b128 v[188:191], v159 offset:18432
	ds_read_b128 v[192:195], v159 offset:19456
	ds_read_b128 v[196:199], v159 offset:20480
	ds_read_b128 v[210:213], v159 offset:21504
	ds_read_b128 v[214:217], v159 offset:22528
	ds_read_b128 v[218:221], v159 offset:23552
	global_load_lds_dwordx4 v[154:155], off
	s_add_i32 m0, s40, 0x2000
	s_add_u32 s40, s14, 0x160000
	v_lshl_add_u64 v[222:223], s[14:15], 0, v[144:145]
	s_addc_u32 s41, s15, 0
	s_add_i32 s42, s42, s22
	global_load_lds_dwordx4 v[222:223], off
	v_lshl_add_u64 v[224:225], s[40:41], 0, v[160:161]
	s_mov_b32 m0, s42
	v_lshl_add_u64 v[226:227], s[16:17], 0, v[146:147]
	global_load_lds_dwordx4 v[224:225], off
	v_lshl_add_u64 v[224:225], s[40:41], 0, v[144:145]
	s_add_i32 m0, s42, 0x2000
	s_nop 0
	global_load_lds_dwordx4 v[224:225], off
	v_lshl_add_u64 v[224:225], s[16:17], 0, v[148:149]
	s_mov_b32 m0, s23
	s_nop 0
	global_load_lds_dwordx4 v[224:225], off
	s_mov_b32 m0, s24
	s_nop 0
	global_load_lds_dwordx4 v[226:227], off
	s_waitcnt vmcnt(8)
	s_waitcnt lgkmcnt(0)
	s_barrier
; #define PG8_STAGE(bufoff, gbase, voff) do { _Pragma("unroll") for (int _i = 0; _i < 2; ++_i) \
;         __builtin_amdgcn_global_load_lds((const unsigned*)((const char*)(gbase) + (voff)[_i]), (LAS unsigned*)(lds + (bufoff) + ldsw + _i * 8192), 16, 0, 0); } while (0)
; #define PG8_LDA(dst, b, h) do { _Pragma("unroll") for (int m = 0; m < 4; ++m) _Pragma("unroll") for (int k = 0; k < 2; ++k) dst[m][k] = *(const LAS bf16x8*)(lds + PG8_SA(b, h) + aoff + m * 2048 + k * 1024); } while (0)
; #define PG8_LDB(dst, b, h) do { _Pragma("unroll") for (int n = 0; n < 2; ++n) _Pragma("unroll") for (int k = 0; k < 2; ++k) dst[n][k] = *(const LAS bf16x8*)(lds + PG8_SB(b, h) + boff + n * 2048 + k * 1024); } while (0)
; #define PG8_MMA(ai, bj, At, Bt) do { __builtin_amdgcn_s_setprio(1); _Pragma("unroll") for (int m = 0; m < 4; ++m) _Pragma("unroll") for (int n = 0; n < 2; ++n) _Pragma("unroll") for (int k = 0; k < 2; ++k) \
;         acc[ai][bj][m][n] = __builtin_amdgcn_mfma_f32_16x16x32_bf16(Bt[n][k], At[m][k], acc[ai][bj][m][n], 0, 0, 0); __builtin_amdgcn_s_setprio(0); } while (0)
; #define PG8_WAIT_V(n) asm volatile("s_waitcnt vmcnt(" #n ")" ::: "memory")
; #define PG8_WAIT_L(n) asm volatile("s_waitcnt lgkmcnt(" #n ")" ::: "memory")
; #define PG8_BAR __builtin_amdgcn_s_barrier()
; #define PG8_SCHED __builtin_amdgcn_sched_barrier(0)
; template <class Epi, class Sched>
; DI void gemm_phase(const int wv, LAS unsigned char* lds, const int lda, const int ldb, const int K, const Sched& S, const Epi& E) {
;     ...
;             PG8_WAIT_V(8); PG8_WAIT_L(0); PG8_BAR; PG8_MMA(1, 0, At, B0); PG8_MMA(1, 1, At, B1); PG8_BAR; PG8_SCHED;
;             PG8_LDB(B0, 1, 0); PG8_LDB(B1, 1, 1); PG8_SCHED; PG8_LDA(At, 1, 0); PG8_STAGE(PG8_SA(0, 1), a2 + hstepA, voffA);
;             PG8_WAIT_V(8); PG8_WAIT_L(0); PG8_BAR; PG8_MMA(0, 0, At, B0); PG8_MMA(0, 1, At, B1); PG8_BAR; PG8_SCHED;
	s_setprio 1
	v_mfma_f32_16x16x32_bf16 v[68:71], v[48:51], v[180:183], v[68:71]
	v_mfma_f32_16x16x32_bf16 v[64:67], v[72:75], v[180:183], v[64:67]
	v_mfma_f32_16x16x32_bf16 v[44:47], v[48:51], v[188:191], v[44:47]
	v_mfma_f32_16x16x32_bf16 v[40:43], v[72:75], v[188:191], v[40:43]
	v_mfma_f32_16x16x32_bf16 v[28:31], v[48:51], v[196:199], v[28:31]
	v_mfma_f32_16x16x32_bf16 v[24:27], v[72:75], v[196:199], v[24:27]
	v_mfma_f32_16x16x32_bf16 v[12:15], v[48:51], v[214:217], v[12:15]
	v_mfma_f32_16x16x32_bf16 v[8:11], v[72:75], v[214:217], v[8:11]
	v_mfma_f32_16x16x32_bf16 v[68:71], v[52:55], v[184:187], v[68:71]
	v_mfma_f32_16x16x32_bf16 v[64:67], v[76:79], v[184:187], v[64:67]
	v_mfma_f32_16x16x32_bf16 v[44:47], v[52:55], v[192:195], v[44:47]
	v_mfma_f32_16x16x32_bf16 v[40:43], v[76:79], v[192:195], v[40:43]
	v_mfma_f32_16x16x32_bf16 v[28:31], v[52:55], v[210:213], v[28:31]
	v_mfma_f32_16x16x32_bf16 v[24:27], v[76:79], v[210:213], v[24:27]
	v_mfma_f32_16x16x32_bf16 v[12:15], v[52:55], v[218:221], v[12:15]
	v_mfma_f32_16x16x32_bf16 v[8:11], v[76:79], v[218:221], v[8:11]
	v_mfma_f32_16x16x32_bf16 v[36:39], v[162:165], v[188:191], v[36:39]
	v_mfma_f32_16x16x32_bf16 v[32:35], v[172:175], v[188:191], v[32:35]
	v_mfma_f32_16x16x32_bf16 v[20:23], v[162:165], v[196:199], v[20:23]
	v_mfma_f32_16x16x32_bf16 v[16:19], v[172:175], v[196:199], v[16:19]
	v_mfma_f32_16x16x32_bf16 v[4:7], v[162:165], v[214:217], v[4:7]
	v_mfma_f32_16x16x32_bf16 v[0:3], v[172:175], v[214:217], v[0:3]
	v_mfma_f32_16x16x32_bf16 v[48:51], v[162:165], v[180:183], v[60:63]
	v_mfma_f32_16x16x32_bf16 v[52:55], v[172:175], v[180:183], v[56:59]
	v_mfma_f32_16x16x32_bf16 v[36:39], v[168:171], v[192:195], v[36:39]
	v_mfma_f32_16x16x32_bf16 v[32:35], v[176:179], v[192:195], v[32:35]
	v_mfma_f32_16x16x32_bf16 v[20:23], v[168:171], v[210:213], v[20:23]
	v_mfma_f32_16x16x32_bf16 v[16:19], v[176:179], v[210:213], v[16:19]
	v_mfma_f32_16x16x32_bf16 v[4:7], v[168:171], v[218:221], v[4:7]
	v_mfma_f32_16x16x32_bf16 v[0:3], v[176:179], v[218:221], v[0:3]
	v_mfma_f32_16x16x32_bf16 v[48:51], v[168:171], v[184:187], v[48:51]
	v_mfma_f32_16x16x32_bf16 v[52:55], v[176:179], v[184:187], v[52:55]
	s_setprio 0
	s_barrier
	s_add_i32 s40, 0, 0x18000
	s_add_i32 s41, 0, 0x1c000
	v_add_u32_e32 v76, s40, v157
	v_add_u32_e32 v176, s41, v157
	ds_read_b128 v[56:59], v76
	ds_read_b128 v[60:63], v76 offset:1024
	ds_read_b128 v[72:75], v76 offset:2048
	ds_read_b128 v[76:79], v76 offset:3072
	ds_read_b128 v[162:165], v176
	ds_read_b128 v[168:171], v176 offset:1024
	ds_read_b128 v[172:175], v176 offset:2048
	ds_read_b128 v[176:179], v176 offset:3072
	s_add_u32 s16, s16, 0x160000
	s_addc_u32 s17, s17, 0
	s_mov_b32 m0, s25
	v_lshl_add_u64 v[228:229], s[16:17], 0, v[148:149]
	ds_read_b128 v[180:183], v159 offset:32768
	ds_read_b128 v[184:187], v159 offset:33792
	ds_read_b128 v[188:191], v159 offset:34816
	ds_read_b128 v[192:195], v159 offset:35840
	ds_read_b128 v[196:199], v159 offset:36864
	ds_read_b128 v[210:213], v159 offset:37888
	ds_read_b128 v[214:217], v159 offset:38912
	ds_read_b128 v[218:221], v159 offset:39936
	global_load_lds_dwordx4 v[228:229], off
	v_lshl_add_u64 v[228:229], s[16:17], 0, v[146:147]
	s_mov_b32 m0, s26
	s_nop 0
	global_load_lds_dwordx4 v[228:229], off
	s_waitcnt vmcnt(8)
	s_waitcnt lgkmcnt(0)
	s_barrier
	s_setprio 1
	v_mfma_f32_16x16x32_bf16 v[140:143], v[56:59], v[180:183], v[140:143]
	v_mfma_f32_16x16x32_bf16 v[136:139], v[72:75], v[180:183], v[136:139]
	v_mfma_f32_16x16x32_bf16 v[124:127], v[56:59], v[188:191], v[124:127]
	v_mfma_f32_16x16x32_bf16 v[120:123], v[72:75], v[188:191], v[120:123]
	v_mfma_f32_16x16x32_bf16 v[116:119], v[56:59], v[196:199], v[116:119]
	v_mfma_f32_16x16x32_bf16 v[112:115], v[72:75], v[196:199], v[112:115]
	v_mfma_f32_16x16x32_bf16 v[100:103], v[56:59], v[214:217], v[100:103]
	v_mfma_f32_16x16x32_bf16 v[96:99], v[72:75], v[214:217], v[96:99]
	v_mfma_f32_16x16x32_bf16 v[140:143], v[60:63], v[184:187], v[140:143]
	v_mfma_f32_16x16x32_bf16 v[136:139], v[76:79], v[184:187], v[136:139]
	v_mfma_f32_16x16x32_bf16 v[124:127], v[60:63], v[192:195], v[124:127]
	v_mfma_f32_16x16x32_bf16 v[120:123], v[76:79], v[192:195], v[120:123]
	v_mfma_f32_16x16x32_bf16 v[116:119], v[60:63], v[210:213], v[116:119]
	v_mfma_f32_16x16x32_bf16 v[112:115], v[76:79], v[210:213], v[112:115]
	v_mfma_f32_16x16x32_bf16 v[100:103], v[60:63], v[218:221], v[100:103]
	v_mfma_f32_16x16x32_bf16 v[96:99], v[76:79], v[218:221], v[96:99]
	v_mfma_f32_16x16x32_bf16 v[132:135], v[162:165], v[180:183], v[132:135]
	v_mfma_f32_16x16x32_bf16 v[128:131], v[172:175], v[180:183], v[128:131]
	v_mfma_f32_16x16x32_bf16 v[108:111], v[162:165], v[188:191], v[108:111]
	v_mfma_f32_16x16x32_bf16 v[104:107], v[172:175], v[188:191], v[104:107]
	v_mfma_f32_16x16x32_bf16 v[92:95], v[162:165], v[196:199], v[92:95]
	v_mfma_f32_16x16x32_bf16 v[88:91], v[172:175], v[196:199], v[88:91]
	v_mfma_f32_16x16x32_bf16 v[84:87], v[162:165], v[214:217], v[84:87]
	v_mfma_f32_16x16x32_bf16 v[80:83], v[172:175], v[214:217], v[80:83]
	v_mfma_f32_16x16x32_bf16 v[132:135], v[168:171], v[184:187], v[132:135]
	v_mfma_f32_16x16x32_bf16 v[128:131], v[176:179], v[184:187], v[128:131]
	v_mfma_f32_16x16x32_bf16 v[108:111], v[168:171], v[192:195], v[108:111]
	v_mfma_f32_16x16x32_bf16 v[104:107], v[176:179], v[192:195], v[104:107]
	v_mfma_f32_16x16x32_bf16 v[92:95], v[168:171], v[210:213], v[92:95]
	v_mfma_f32_16x16x32_bf16 v[88:91], v[176:179], v[210:213], v[88:91]
	v_mfma_f32_16x16x32_bf16 v[84:87], v[168:171], v[218:221], v[84:87]
	v_mfma_f32_16x16x32_bf16 v[80:83], v[176:179], v[218:221], v[80:83]
	s_setprio 0
	s_barrier
; #define PG8_STAGE(bufoff, gbase, voff) do { _Pragma("unroll") for (int _i = 0; _i < 2; ++_i) \
;         __builtin_amdgcn_global_load_lds((const unsigned*)((const char*)(gbase) + (voff)[_i]), (LAS unsigned*)(lds + (bufoff) + ldsw + _i * 8192), 16, 0, 0); } while (0)
; #define PG8_LDA(dst, b, h) do { _Pragma("unroll") for (int m = 0; m < 4; ++m) _Pragma("unroll") for (int k = 0; k < 2; ++k) dst[m][k] = *(const LAS bf16x8*)(lds + PG8_SA(b, h) + aoff + m * 2048 + k * 1024); } while (0)
; #define PG8_MMA(ai, bj, At, Bt) do { __builtin_amdgcn_s_setprio(1); _Pragma("unroll") for (int m = 0; m < 4; ++m) _Pragma("unroll") for (int n = 0; n < 2; ++n) _Pragma("unroll") for (int k = 0; k < 2; ++k) \
;         acc[ai][bj][m][n] = __builtin_amdgcn_mfma_f32_16x16x32_bf16(Bt[n][k], At[m][k], acc[ai][bj][m][n], 0, 0, 0); __builtin_amdgcn_s_setprio(0); } while (0)
; #define PG8_WAIT_V(n) asm volatile("s_waitcnt vmcnt(" #n ")" ::: "memory")
; #define PG8_WAIT_L(n) asm volatile("s_waitcnt lgkmcnt(" #n ")" ::: "memory")
; #define PG8_BAR __builtin_amdgcn_s_barrier()
; #define PG8_SCHED __builtin_amdgcn_sched_barrier(0)
; template <class Epi, class Sched>
; DI void gemm_phase(const int wv, LAS unsigned char* lds, const int lda, const int ldb, const int K, const Sched& S, const Epi& E) {
;     ...
;             PG8_LDA(At, 1, 1); PG8_STAGE(PG8_SB(1, 0), b3, voffB); PG8_STAGE(PG8_SB(1, 1), b3 + hstepB, voffB); PG8_STAGE(PG8_SA(1, 0), a3, voffA);
;             PG8_WAIT_V(8); PG8_WAIT_L(0); PG8_BAR; PG8_MMA(1, 0, At, B0); PG8_MMA(1, 1, At, B1); PG8_BAR; PG8_SCHED;
;         }
;         if (wr == 0) PG8_BAR;
	s_add_i32 s16, s40, s22
	v_lshl_add_u64 v[154:155], v[154:155], 0, s[78:79]
	s_mov_b32 m0, s16
	ds_read_b128 v[180:183], v159 offset:49152
	ds_read_b128 v[184:187], v159 offset:50176
	ds_read_b128 v[188:191], v159 offset:51200
	ds_read_b128 v[192:195], v159 offset:52224
	ds_read_b128 v[196:199], v159 offset:53248
	ds_read_b128 v[210:213], v159 offset:54272
	ds_read_b128 v[214:217], v159 offset:55296
	ds_read_b128 v[218:221], v159 offset:56320
	global_load_lds_dwordx4 v[154:155], off
	s_add_i32 m0, s16, 0x2000
	s_add_u32 s14, s14, 0x160080
	v_lshl_add_u64 v[154:155], v[222:223], 0, s[78:79]
	s_addc_u32 s15, s15, 0
	s_add_i32 s16, s41, s22
	global_load_lds_dwordx4 v[154:155], off
	v_lshl_add_u64 v[154:155], s[14:15], 0, v[160:161]
	s_mov_b32 m0, s16
	s_nop 0
	global_load_lds_dwordx4 v[154:155], off
	v_lshl_add_u64 v[154:155], s[14:15], 0, v[144:145]
	s_add_i32 m0, s16, 0x2000
	s_nop 0
	global_load_lds_dwordx4 v[154:155], off
	v_lshl_add_u64 v[154:155], v[224:225], 0, s[78:79]
	s_mov_b32 m0, s29
	s_nop 0
	global_load_lds_dwordx4 v[154:155], off
	v_lshl_add_u64 v[154:155], v[226:227], 0, s[78:79]
	s_mov_b32 m0, s30
	s_nop 0
	global_load_lds_dwordx4 v[154:155], off
	s_waitcnt vmcnt(8)
	s_waitcnt lgkmcnt(0)
	s_barrier
	s_setprio 1
	v_mfma_f32_16x16x32_bf16 v[68:71], v[56:59], v[180:183], v[68:71]
	v_mfma_f32_16x16x32_bf16 v[64:67], v[72:75], v[180:183], v[64:67]
	v_mfma_f32_16x16x32_bf16 v[44:47], v[56:59], v[188:191], v[44:47]
	v_mfma_f32_16x16x32_bf16 v[40:43], v[72:75], v[188:191], v[40:43]
	v_mfma_f32_16x16x32_bf16 v[28:31], v[56:59], v[196:199], v[28:31]
	v_mfma_f32_16x16x32_bf16 v[24:27], v[72:75], v[196:199], v[24:27]
	v_mfma_f32_16x16x32_bf16 v[12:15], v[56:59], v[214:217], v[12:15]
	v_mfma_f32_16x16x32_bf16 v[8:11], v[72:75], v[214:217], v[8:11]
	v_mfma_f32_16x16x32_bf16 v[68:71], v[60:63], v[184:187], v[68:71]
	v_mfma_f32_16x16x32_bf16 v[64:67], v[76:79], v[184:187], v[64:67]
	v_mfma_f32_16x16x32_bf16 v[44:47], v[60:63], v[192:195], v[44:47]
	v_mfma_f32_16x16x32_bf16 v[40:43], v[76:79], v[192:195], v[40:43]
	v_mfma_f32_16x16x32_bf16 v[28:31], v[60:63], v[210:213], v[28:31]
	v_mfma_f32_16x16x32_bf16 v[24:27], v[76:79], v[210:213], v[24:27]
	v_mfma_f32_16x16x32_bf16 v[12:15], v[60:63], v[218:221], v[12:15]
	v_mfma_f32_16x16x32_bf16 v[8:11], v[76:79], v[218:221], v[8:11]
	v_mfma_f32_16x16x32_bf16 v[48:51], v[162:165], v[180:183], v[48:51]
	v_mfma_f32_16x16x32_bf16 v[60:63], v[168:171], v[184:187], v[48:51]
	v_mfma_f32_16x16x32_bf16 v[48:51], v[172:175], v[180:183], v[52:55]
	v_mfma_f32_16x16x32_bf16 v[36:39], v[162:165], v[188:191], v[36:39]
	v_mfma_f32_16x16x32_bf16 v[32:35], v[172:175], v[188:191], v[32:35]
	v_mfma_f32_16x16x32_bf16 v[20:23], v[162:165], v[196:199], v[20:23]
	v_mfma_f32_16x16x32_bf16 v[16:19], v[172:175], v[196:199], v[16:19]
	v_mfma_f32_16x16x32_bf16 v[4:7], v[162:165], v[214:217], v[4:7]
	v_mfma_f32_16x16x32_bf16 v[0:3], v[172:175], v[214:217], v[0:3]
	v_mfma_f32_16x16x32_bf16 v[56:59], v[176:179], v[184:187], v[48:51]
	v_mfma_f32_16x16x32_bf16 v[36:39], v[168:171], v[192:195], v[36:39]
	v_mfma_f32_16x16x32_bf16 v[32:35], v[176:179], v[192:195], v[32:35]
	v_mfma_f32_16x16x32_bf16 v[20:23], v[168:171], v[210:213], v[20:23]
	v_mfma_f32_16x16x32_bf16 v[16:19], v[176:179], v[210:213], v[16:19]
	v_mfma_f32_16x16x32_bf16 v[4:7], v[168:171], v[218:221], v[4:7]
	v_mfma_f32_16x16x32_bf16 v[0:3], v[176:179], v[218:221], v[0:3]
	s_setprio 0
	s_barrier
	s_add_i32 s39, s39, 2
	s_add_u32 s37, s37, 0x100
	s_addc_u32 s38, s38, 0
	s_add_u32 s12, s12, 0x100
	s_addc_u32 s13, s13, 0
	s_cmpk_gt_u32 s39, 0x55
	s_cbranch_scc0 .LBB0_906
	s_and_b64 vcc, exec, s[6:7]
	s_cbranch_vccz .LBB0_909
	s_barrier
